# v048 + W_IN epilogue row-group addresses from group 0 (no per-group 64-bit mad) + MERGE non-final epilogue dead store blocks and pointer math removed + TOPK ctx items stop after the 256-key levels
# baseline (speedup 1.0000x reference)
.LBB0_215:
	v_cvt_pk_bf16_f32 v110, v110, v111
	v_cvt_pk_bf16_f32 v111, v112, v113
	v_cvt_pk_bf16_f32 v112, v106, v107
	s_mul_i32 s98, s85, 16
	s_mov_b32 s99, 0
	v_lshl_add_u64 v[106:107], v[122:123], 0, s[98:99]
	s_and_b64 vcc, exec, s[6:7]
	v_cvt_pk_bf16_f32 v113, v108, v109
	global_store_dwordx4 v[106:107], v[110:113], off
	s_cbranch_vccnz .LBB0_217
	s_mov_b32 s98, 0xbfb8aa3b
	v_pk_mul_f32 v[102:103], v[102:103], s[98:99] op_sel_hi:[1,0]
	v_pk_mul_f32 v[104:105], v[104:105], s[98:99] op_sel_hi:[1,0]
	v_pk_mul_f32 v[98:99], v[98:99], s[98:99] op_sel_hi:[1,0]
	v_pk_mul_f32 v[100:101], v[100:101], s[98:99] op_sel_hi:[1,0]
	v_exp_f32_e32 v102, v102
	v_exp_f32_e32 v103, v103
	v_exp_f32_e32 v104, v104
	v_exp_f32_e32 v105, v105
	v_exp_f32_e32 v98, v98
	v_exp_f32_e32 v99, v99
	v_exp_f32_e32 v100, v100
	v_exp_f32_e32 v101, v101
	v_pk_add_f32 v[102:103], v[102:103], 1.0 op_sel_hi:[1,0]
	v_pk_add_f32 v[104:105], v[104:105], 1.0 op_sel_hi:[1,0]
	v_pk_add_f32 v[98:99], v[98:99], 1.0 op_sel_hi:[1,0]
	v_pk_add_f32 v[100:101], v[100:101], 1.0 op_sel_hi:[1,0]
	v_rcp_f32_e32 v102, v102
	v_rcp_f32_e32 v103, v103
	v_rcp_f32_e32 v104, v104
	v_rcp_f32_e32 v105, v105
	v_rcp_f32_e32 v98, v98
	v_rcp_f32_e32 v99, v99
	v_rcp_f32_e32 v100, v100
	v_rcp_f32_e32 v101, v101

.LBB0_219:
	v_cvt_pk_bf16_f32 v94, v94, v95
	v_cvt_pk_bf16_f32 v95, v96, v97
	v_cvt_pk_bf16_f32 v96, v90, v91
	s_mul_i32 s98, s85, 32
	s_mov_b32 s99, 0
	v_lshl_add_u64 v[90:91], v[122:123], 0, s[98:99]
	s_and_b64 vcc, exec, s[6:7]
	v_cvt_pk_bf16_f32 v97, v92, v93
	global_store_dwordx4 v[90:91], v[94:97], off
	s_cbranch_vccnz .LBB0_221
	s_mov_b32 s98, 0xbfb8aa3b
	v_pk_mul_f32 v[86:87], v[86:87], s[98:99] op_sel_hi:[1,0]
	v_pk_mul_f32 v[88:89], v[88:89], s[98:99] op_sel_hi:[1,0]
	v_pk_mul_f32 v[82:83], v[82:83], s[98:99] op_sel_hi:[1,0]
	v_pk_mul_f32 v[84:85], v[84:85], s[98:99] op_sel_hi:[1,0]
	v_exp_f32_e32 v86, v86
	v_exp_f32_e32 v87, v87
	v_exp_f32_e32 v88, v88
	v_exp_f32_e32 v89, v89
	v_exp_f32_e32 v82, v82
	v_exp_f32_e32 v83, v83
	v_exp_f32_e32 v84, v84
	v_exp_f32_e32 v85, v85
	v_pk_add_f32 v[86:87], v[86:87], 1.0 op_sel_hi:[1,0]
	v_pk_add_f32 v[88:89], v[88:89], 1.0 op_sel_hi:[1,0]
	v_pk_add_f32 v[82:83], v[82:83], 1.0 op_sel_hi:[1,0]
	v_pk_add_f32 v[84:85], v[84:85], 1.0 op_sel_hi:[1,0]
	v_rcp_f32_e32 v86, v86
	v_rcp_f32_e32 v87, v87
	v_rcp_f32_e32 v88, v88
	v_rcp_f32_e32 v89, v89
	v_rcp_f32_e32 v82, v82
	v_rcp_f32_e32 v83, v83
	v_rcp_f32_e32 v84, v84
	v_rcp_f32_e32 v85, v85

.LBB0_223:
	v_cvt_pk_bf16_f32 v78, v78, v79
	v_cvt_pk_bf16_f32 v79, v80, v81
	v_cvt_pk_bf16_f32 v80, v74, v75
	s_mul_i32 s98, s85, 48
	s_mov_b32 s99, 0
	v_lshl_add_u64 v[74:75], v[122:123], 0, s[98:99]
	s_and_b64 vcc, exec, s[6:7]
	v_cvt_pk_bf16_f32 v81, v76, v77
	global_store_dwordx4 v[74:75], v[78:81], off
	s_cbranch_vccnz .LBB0_225
	s_mov_b32 s98, 0xbfb8aa3b
	v_pk_mul_f32 v[70:71], v[70:71], s[98:99] op_sel_hi:[1,0]
	v_pk_mul_f32 v[72:73], v[72:73], s[98:99] op_sel_hi:[1,0]
	v_pk_mul_f32 v[66:67], v[66:67], s[98:99] op_sel_hi:[1,0]
	v_pk_mul_f32 v[68:69], v[68:69], s[98:99] op_sel_hi:[1,0]
	v_exp_f32_e32 v70, v70
	v_exp_f32_e32 v71, v71
	v_exp_f32_e32 v72, v72
	v_exp_f32_e32 v73, v73
	v_exp_f32_e32 v66, v66
	v_exp_f32_e32 v67, v67
	v_exp_f32_e32 v68, v68
	v_exp_f32_e32 v69, v69
	v_pk_add_f32 v[70:71], v[70:71], 1.0 op_sel_hi:[1,0]
	v_pk_add_f32 v[72:73], v[72:73], 1.0 op_sel_hi:[1,0]
	v_pk_add_f32 v[66:67], v[66:67], 1.0 op_sel_hi:[1,0]
	v_pk_add_f32 v[68:69], v[68:69], 1.0 op_sel_hi:[1,0]
	v_rcp_f32_e32 v70, v70
	v_rcp_f32_e32 v71, v71
	v_rcp_f32_e32 v72, v72
	v_rcp_f32_e32 v73, v73
	v_rcp_f32_e32 v66, v66
	v_rcp_f32_e32 v67, v67
	v_rcp_f32_e32 v68, v68
	v_rcp_f32_e32 v69, v69

.LBB0_227:
	v_cvt_pk_bf16_f32 v62, v62, v63
	v_cvt_pk_bf16_f32 v63, v64, v65
	v_cvt_pk_bf16_f32 v64, v58, v59
	s_mul_i32 s98, s85, 128
	s_mov_b32 s99, 0
	v_lshl_add_u64 v[58:59], v[122:123], 0, s[98:99]
	s_and_b64 vcc, exec, s[6:7]
	v_cvt_pk_bf16_f32 v65, v60, v61
	global_store_dwordx4 v[58:59], v[62:65], off
	s_cbranch_vccnz .LBB0_229
	s_mov_b32 s98, 0xbfb8aa3b
	v_pk_mul_f32 v[54:55], v[54:55], s[98:99] op_sel_hi:[1,0]
	v_pk_mul_f32 v[56:57], v[56:57], s[98:99] op_sel_hi:[1,0]
	v_pk_mul_f32 v[50:51], v[50:51], s[98:99] op_sel_hi:[1,0]
	v_pk_mul_f32 v[52:53], v[52:53], s[98:99] op_sel_hi:[1,0]
	v_exp_f32_e32 v54, v54
	v_exp_f32_e32 v55, v55
	v_exp_f32_e32 v56, v56
	v_exp_f32_e32 v57, v57
	v_exp_f32_e32 v50, v50
	v_exp_f32_e32 v51, v51
	v_exp_f32_e32 v52, v52
	v_exp_f32_e32 v53, v53
	v_pk_add_f32 v[54:55], v[54:55], 1.0 op_sel_hi:[1,0]
	v_pk_add_f32 v[56:57], v[56:57], 1.0 op_sel_hi:[1,0]
	v_pk_add_f32 v[50:51], v[50:51], 1.0 op_sel_hi:[1,0]
	v_pk_add_f32 v[52:53], v[52:53], 1.0 op_sel_hi:[1,0]
	v_rcp_f32_e32 v54, v54
	v_rcp_f32_e32 v55, v55
	v_rcp_f32_e32 v56, v56
	v_rcp_f32_e32 v57, v57
	v_rcp_f32_e32 v50, v50
	v_rcp_f32_e32 v51, v51
	v_rcp_f32_e32 v52, v52
	v_rcp_f32_e32 v53, v53

.LBB0_231:
	v_cvt_pk_bf16_f32 v46, v46, v47
	v_cvt_pk_bf16_f32 v47, v48, v49
	v_cvt_pk_bf16_f32 v48, v42, v43
	s_mul_i32 s98, s85, 144
	s_mov_b32 s99, 0
	v_lshl_add_u64 v[42:43], v[122:123], 0, s[98:99]
	s_and_b64 vcc, exec, s[6:7]
	v_cvt_pk_bf16_f32 v49, v44, v45
	global_store_dwordx4 v[42:43], v[46:49], off
	s_cbranch_vccnz .LBB0_233
	s_mov_b32 s98, 0xbfb8aa3b
	v_pk_mul_f32 v[38:39], v[38:39], s[98:99] op_sel_hi:[1,0]
	v_pk_mul_f32 v[40:41], v[40:41], s[98:99] op_sel_hi:[1,0]
	v_pk_mul_f32 v[34:35], v[34:35], s[98:99] op_sel_hi:[1,0]
	v_pk_mul_f32 v[36:37], v[36:37], s[98:99] op_sel_hi:[1,0]
	v_exp_f32_e32 v38, v38
	v_exp_f32_e32 v39, v39
	v_exp_f32_e32 v40, v40
	v_exp_f32_e32 v41, v41
	v_exp_f32_e32 v34, v34
	v_exp_f32_e32 v35, v35
	v_exp_f32_e32 v36, v36
	v_exp_f32_e32 v37, v37
	v_pk_add_f32 v[38:39], v[38:39], 1.0 op_sel_hi:[1,0]
	v_pk_add_f32 v[40:41], v[40:41], 1.0 op_sel_hi:[1,0]
	v_pk_add_f32 v[34:35], v[34:35], 1.0 op_sel_hi:[1,0]
	v_pk_add_f32 v[36:37], v[36:37], 1.0 op_sel_hi:[1,0]
	v_rcp_f32_e32 v38, v38
	v_rcp_f32_e32 v39, v39
	v_rcp_f32_e32 v40, v40
	v_rcp_f32_e32 v41, v41
	v_rcp_f32_e32 v34, v34
	v_rcp_f32_e32 v35, v35
	v_rcp_f32_e32 v36, v36
	v_rcp_f32_e32 v37, v37

.LBB0_235:
	v_cvt_pk_bf16_f32 v22, v22, v23
	v_cvt_pk_bf16_f32 v23, v24, v25
	v_cvt_pk_bf16_f32 v24, v18, v19
	s_mul_i32 s98, s85, 160
	s_mov_b32 s99, 0
	v_lshl_add_u64 v[18:19], v[122:123], 0, s[98:99]
	s_and_b64 vcc, exec, s[6:7]
	v_cvt_pk_bf16_f32 v25, v20, v21
	global_store_dwordx4 v[18:19], v[22:25], off
	s_cbranch_vccnz .LBB0_237
	v_mul_f32_e32 v20, 0xbfb8aa3b, v26
	v_exp_f32_e32 v20, v20
	v_mul_f32_e32 v21, 0xbfb8aa3b, v27
	v_exp_f32_e32 v21, v21
	v_mul_f32_e32 v22, 0xbfb8aa3b, v29
	v_add_f32_e32 v20, 1.0, v20
	v_rcp_f32_e32 v26, v20
	v_mul_f32_e32 v20, 0xbfb8aa3b, v28
	v_exp_f32_e32 v20, v20
	v_exp_f32_e32 v22, v22
	v_add_f32_e32 v21, 1.0, v21
	v_rcp_f32_e32 v27, v21
	v_add_f32_e32 v20, 1.0, v20
	v_mul_f32_e32 v21, 0xbfb8aa3b, v30
	v_rcp_f32_e32 v28, v20
	v_add_f32_e32 v20, 1.0, v22
	v_exp_f32_e32 v21, v21
	v_mul_f32_e32 v22, 0xbfb8aa3b, v31
	v_exp_f32_e32 v22, v22
	v_rcp_f32_e32 v29, v20
	v_add_f32_e32 v20, 1.0, v21
	v_mul_f32_e32 v21, 0xbfb8aa3b, v32
	v_rcp_f32_e32 v30, v20
	v_add_f32_e32 v20, 1.0, v22
	v_exp_f32_e32 v21, v21
	v_mul_f32_e32 v22, 0xbfb8aa3b, v33
	v_exp_f32_e32 v22, v22
	v_rcp_f32_e32 v31, v20
	v_add_f32_e32 v20, 1.0, v21
	v_rcp_f32_e32 v32, v20
	v_add_f32_e32 v20, 1.0, v22
	v_rcp_f32_e32 v33, v20

.LBB0_239:
	s_nop 0
	v_cvt_pk_bf16_f32 v6, v6, v7
	v_cvt_pk_bf16_f32 v7, v8, v9
	v_cvt_pk_bf16_f32 v8, v2, v3
	s_mul_i32 s98, s85, 176
	s_mov_b32 s99, 0
	v_lshl_add_u64 v[2:3], v[122:123], 0, s[98:99]
	s_and_b64 vcc, exec, s[6:7]
	v_cvt_pk_bf16_f32 v9, v4, v5
	global_store_dwordx4 v[2:3], v[6:9], off
	s_cbranch_vccnz .LBB0_241
	v_mul_f32_e32 v4, 0xbfb8aa3b, v10
	v_exp_f32_e32 v4, v4
	v_mul_f32_e32 v5, 0xbfb8aa3b, v11
	v_exp_f32_e32 v5, v5
	v_mul_f32_e32 v6, 0xbfb8aa3b, v13
	v_add_f32_e32 v4, 1.0, v4
	v_rcp_f32_e32 v10, v4
	v_mul_f32_e32 v4, 0xbfb8aa3b, v12
	v_exp_f32_e32 v4, v4
	v_exp_f32_e32 v6, v6
	v_add_f32_e32 v5, 1.0, v5
	v_rcp_f32_e32 v11, v5
	v_add_f32_e32 v4, 1.0, v4
	v_mul_f32_e32 v5, 0xbfb8aa3b, v14
	v_rcp_f32_e32 v12, v4
	v_add_f32_e32 v4, 1.0, v6
	v_exp_f32_e32 v5, v5
	v_mul_f32_e32 v6, 0xbfb8aa3b, v15
	v_exp_f32_e32 v6, v6
	v_rcp_f32_e32 v13, v4
	v_add_f32_e32 v4, 1.0, v5
	v_mul_f32_e32 v5, 0xbfb8aa3b, v16
	v_rcp_f32_e32 v14, v4
	v_add_f32_e32 v4, 1.0, v6
	v_exp_f32_e32 v5, v5
	v_mul_f32_e32 v6, 0xbfb8aa3b, v17
	v_exp_f32_e32 v6, v6
	v_rcp_f32_e32 v15, v4
	v_add_f32_e32 v4, 1.0, v5
	v_rcp_f32_e32 v16, v4
	v_add_f32_e32 v4, 1.0, v6
	v_rcp_f32_e32 v17, v4

.LBB0_273:
	v_cvt_pk_bf16_f32 v110, v110, v111
	v_cvt_pk_bf16_f32 v111, v112, v113
	v_cvt_pk_bf16_f32 v112, v106, v107
	s_mul_i32 s98, s85, 16
	s_mov_b32 s99, 0
	v_lshl_add_u64 v[106:107], v[122:123], 0, s[98:99]
	s_and_b64 vcc, exec, s[4:5]
	v_cvt_pk_bf16_f32 v113, v108, v109
	global_store_dwordx4 v[106:107], v[110:113], off
	s_cbranch_vccnz .LBB0_275
	s_mov_b32 s98, 0xbfb8aa3b
	v_pk_mul_f32 v[102:103], v[102:103], s[98:99] op_sel_hi:[1,0]
	v_pk_mul_f32 v[104:105], v[104:105], s[98:99] op_sel_hi:[1,0]
	v_pk_mul_f32 v[98:99], v[98:99], s[98:99] op_sel_hi:[1,0]
	v_pk_mul_f32 v[100:101], v[100:101], s[98:99] op_sel_hi:[1,0]
	v_exp_f32_e32 v102, v102
	v_exp_f32_e32 v103, v103
	v_exp_f32_e32 v104, v104
	v_exp_f32_e32 v105, v105
	v_exp_f32_e32 v98, v98
	v_exp_f32_e32 v99, v99
	v_exp_f32_e32 v100, v100
	v_exp_f32_e32 v101, v101
	v_pk_add_f32 v[102:103], v[102:103], 1.0 op_sel_hi:[1,0]
	v_pk_add_f32 v[104:105], v[104:105], 1.0 op_sel_hi:[1,0]
	v_pk_add_f32 v[98:99], v[98:99], 1.0 op_sel_hi:[1,0]
	v_pk_add_f32 v[100:101], v[100:101], 1.0 op_sel_hi:[1,0]
	v_rcp_f32_e32 v102, v102
	v_rcp_f32_e32 v103, v103
	v_rcp_f32_e32 v104, v104
	v_rcp_f32_e32 v105, v105
	v_rcp_f32_e32 v98, v98
	v_rcp_f32_e32 v99, v99
	v_rcp_f32_e32 v100, v100
	v_rcp_f32_e32 v101, v101

.LBB0_277:
	v_cvt_pk_bf16_f32 v94, v94, v95
	v_cvt_pk_bf16_f32 v95, v96, v97
	v_cvt_pk_bf16_f32 v96, v90, v91
	s_mul_i32 s98, s85, 32
	s_mov_b32 s99, 0
	v_lshl_add_u64 v[90:91], v[122:123], 0, s[98:99]
	s_and_b64 vcc, exec, s[4:5]
	v_cvt_pk_bf16_f32 v97, v92, v93
	global_store_dwordx4 v[90:91], v[94:97], off
	s_cbranch_vccnz .LBB0_279
	s_mov_b32 s98, 0xbfb8aa3b
	v_pk_mul_f32 v[86:87], v[86:87], s[98:99] op_sel_hi:[1,0]
	v_pk_mul_f32 v[88:89], v[88:89], s[98:99] op_sel_hi:[1,0]
	v_pk_mul_f32 v[82:83], v[82:83], s[98:99] op_sel_hi:[1,0]
	v_pk_mul_f32 v[84:85], v[84:85], s[98:99] op_sel_hi:[1,0]
	v_exp_f32_e32 v86, v86
	v_exp_f32_e32 v87, v87
	v_exp_f32_e32 v88, v88
	v_exp_f32_e32 v89, v89
	v_exp_f32_e32 v82, v82
	v_exp_f32_e32 v83, v83
	v_exp_f32_e32 v84, v84
	v_exp_f32_e32 v85, v85
	v_pk_add_f32 v[86:87], v[86:87], 1.0 op_sel_hi:[1,0]
	v_pk_add_f32 v[88:89], v[88:89], 1.0 op_sel_hi:[1,0]
	v_pk_add_f32 v[82:83], v[82:83], 1.0 op_sel_hi:[1,0]
	v_pk_add_f32 v[84:85], v[84:85], 1.0 op_sel_hi:[1,0]
	v_rcp_f32_e32 v86, v86
	v_rcp_f32_e32 v87, v87
	v_rcp_f32_e32 v88, v88
	v_rcp_f32_e32 v89, v89
	v_rcp_f32_e32 v82, v82
	v_rcp_f32_e32 v83, v83
	v_rcp_f32_e32 v84, v84
	v_rcp_f32_e32 v85, v85

.LBB0_281:
	v_cvt_pk_bf16_f32 v78, v78, v79
	v_cvt_pk_bf16_f32 v79, v80, v81
	v_cvt_pk_bf16_f32 v80, v74, v75
	s_mul_i32 s98, s85, 48
	s_mov_b32 s99, 0
	v_lshl_add_u64 v[74:75], v[122:123], 0, s[98:99]
	s_and_b64 vcc, exec, s[4:5]
	v_cvt_pk_bf16_f32 v81, v76, v77
	global_store_dwordx4 v[74:75], v[78:81], off
	s_cbranch_vccnz .LBB0_283
	s_mov_b32 s98, 0xbfb8aa3b
	v_pk_mul_f32 v[70:71], v[70:71], s[98:99] op_sel_hi:[1,0]
	v_pk_mul_f32 v[72:73], v[72:73], s[98:99] op_sel_hi:[1,0]
	v_pk_mul_f32 v[66:67], v[66:67], s[98:99] op_sel_hi:[1,0]
	v_pk_mul_f32 v[68:69], v[68:69], s[98:99] op_sel_hi:[1,0]
	v_exp_f32_e32 v70, v70
	v_exp_f32_e32 v71, v71
	v_exp_f32_e32 v72, v72
	v_exp_f32_e32 v73, v73
	v_exp_f32_e32 v66, v66
	v_exp_f32_e32 v67, v67
	v_exp_f32_e32 v68, v68
	v_exp_f32_e32 v69, v69
	v_pk_add_f32 v[70:71], v[70:71], 1.0 op_sel_hi:[1,0]
	v_pk_add_f32 v[72:73], v[72:73], 1.0 op_sel_hi:[1,0]
	v_pk_add_f32 v[66:67], v[66:67], 1.0 op_sel_hi:[1,0]
	v_pk_add_f32 v[68:69], v[68:69], 1.0 op_sel_hi:[1,0]
	v_rcp_f32_e32 v70, v70
	v_rcp_f32_e32 v71, v71
	v_rcp_f32_e32 v72, v72
	v_rcp_f32_e32 v73, v73
	v_rcp_f32_e32 v66, v66
	v_rcp_f32_e32 v67, v67
	v_rcp_f32_e32 v68, v68
	v_rcp_f32_e32 v69, v69

.LBB0_285:
	v_cvt_pk_bf16_f32 v62, v62, v63
	v_cvt_pk_bf16_f32 v63, v64, v65
	v_cvt_pk_bf16_f32 v64, v58, v59
	s_mul_i32 s98, s85, 128
	s_mov_b32 s99, 0
	v_lshl_add_u64 v[58:59], v[122:123], 0, s[98:99]
	s_and_b64 vcc, exec, s[4:5]
	v_cvt_pk_bf16_f32 v65, v60, v61
	global_store_dwordx4 v[58:59], v[62:65], off
	s_cbranch_vccnz .LBB0_287
	s_mov_b32 s98, 0xbfb8aa3b
	v_pk_mul_f32 v[54:55], v[54:55], s[98:99] op_sel_hi:[1,0]
	v_pk_mul_f32 v[56:57], v[56:57], s[98:99] op_sel_hi:[1,0]
	v_pk_mul_f32 v[50:51], v[50:51], s[98:99] op_sel_hi:[1,0]
	v_pk_mul_f32 v[52:53], v[52:53], s[98:99] op_sel_hi:[1,0]
	v_exp_f32_e32 v54, v54
	v_exp_f32_e32 v55, v55
	v_exp_f32_e32 v56, v56
	v_exp_f32_e32 v57, v57
	v_exp_f32_e32 v50, v50
	v_exp_f32_e32 v51, v51
	v_exp_f32_e32 v52, v52
	v_exp_f32_e32 v53, v53
	v_pk_add_f32 v[54:55], v[54:55], 1.0 op_sel_hi:[1,0]
	v_pk_add_f32 v[56:57], v[56:57], 1.0 op_sel_hi:[1,0]
	v_pk_add_f32 v[50:51], v[50:51], 1.0 op_sel_hi:[1,0]
	v_pk_add_f32 v[52:53], v[52:53], 1.0 op_sel_hi:[1,0]
	v_rcp_f32_e32 v54, v54
	v_rcp_f32_e32 v55, v55
	v_rcp_f32_e32 v56, v56
	v_rcp_f32_e32 v57, v57
	v_rcp_f32_e32 v50, v50
	v_rcp_f32_e32 v51, v51
	v_rcp_f32_e32 v52, v52
	v_rcp_f32_e32 v53, v53

.LBB0_289:
	v_cvt_pk_bf16_f32 v46, v46, v47
	v_cvt_pk_bf16_f32 v47, v48, v49
	v_cvt_pk_bf16_f32 v48, v42, v43
	s_mul_i32 s98, s85, 144
	s_mov_b32 s99, 0
	v_lshl_add_u64 v[42:43], v[122:123], 0, s[98:99]
	s_and_b64 vcc, exec, s[4:5]
	v_cvt_pk_bf16_f32 v49, v44, v45
	global_store_dwordx4 v[42:43], v[46:49], off
	s_cbranch_vccnz .LBB0_291
	s_mov_b32 s98, 0xbfb8aa3b
	v_pk_mul_f32 v[38:39], v[38:39], s[98:99] op_sel_hi:[1,0]
	v_pk_mul_f32 v[40:41], v[40:41], s[98:99] op_sel_hi:[1,0]
	v_pk_mul_f32 v[34:35], v[34:35], s[98:99] op_sel_hi:[1,0]
	v_pk_mul_f32 v[36:37], v[36:37], s[98:99] op_sel_hi:[1,0]
	v_exp_f32_e32 v38, v38
	v_exp_f32_e32 v39, v39
	v_exp_f32_e32 v40, v40
	v_exp_f32_e32 v41, v41
	v_exp_f32_e32 v34, v34
	v_exp_f32_e32 v35, v35
	v_exp_f32_e32 v36, v36
	v_exp_f32_e32 v37, v37
	v_pk_add_f32 v[38:39], v[38:39], 1.0 op_sel_hi:[1,0]
	v_pk_add_f32 v[40:41], v[40:41], 1.0 op_sel_hi:[1,0]
	v_pk_add_f32 v[34:35], v[34:35], 1.0 op_sel_hi:[1,0]
	v_pk_add_f32 v[36:37], v[36:37], 1.0 op_sel_hi:[1,0]
	v_rcp_f32_e32 v38, v38
	v_rcp_f32_e32 v39, v39
	v_rcp_f32_e32 v40, v40
	v_rcp_f32_e32 v41, v41
	v_rcp_f32_e32 v34, v34
	v_rcp_f32_e32 v35, v35
	v_rcp_f32_e32 v36, v36
	v_rcp_f32_e32 v37, v37

.LBB0_293:
	v_cvt_pk_bf16_f32 v22, v22, v23
	v_cvt_pk_bf16_f32 v23, v24, v25
	v_cvt_pk_bf16_f32 v24, v18, v19
	s_mul_i32 s98, s85, 160
	s_mov_b32 s99, 0
	v_lshl_add_u64 v[18:19], v[122:123], 0, s[98:99]
	s_and_b64 vcc, exec, s[4:5]
	v_cvt_pk_bf16_f32 v25, v20, v21
	global_store_dwordx4 v[18:19], v[22:25], off
	s_cbranch_vccnz .LBB0_295
	v_mul_f32_e32 v20, 0xbfb8aa3b, v26
	v_exp_f32_e32 v20, v20
	v_mul_f32_e32 v21, 0xbfb8aa3b, v27
	v_exp_f32_e32 v21, v21
	v_mul_f32_e32 v22, 0xbfb8aa3b, v29
	v_add_f32_e32 v20, 1.0, v20
	v_rcp_f32_e32 v26, v20
	v_mul_f32_e32 v20, 0xbfb8aa3b, v28
	v_exp_f32_e32 v20, v20
	v_exp_f32_e32 v22, v22
	v_add_f32_e32 v21, 1.0, v21
	v_rcp_f32_e32 v27, v21
	v_add_f32_e32 v20, 1.0, v20
	v_mul_f32_e32 v21, 0xbfb8aa3b, v30
	v_rcp_f32_e32 v28, v20
	v_add_f32_e32 v20, 1.0, v22
	v_exp_f32_e32 v21, v21
	v_mul_f32_e32 v22, 0xbfb8aa3b, v31
	v_exp_f32_e32 v22, v22
	v_rcp_f32_e32 v29, v20
	v_add_f32_e32 v20, 1.0, v21
	v_mul_f32_e32 v21, 0xbfb8aa3b, v32
	v_rcp_f32_e32 v30, v20
	v_add_f32_e32 v20, 1.0, v22
	v_exp_f32_e32 v21, v21
	v_mul_f32_e32 v22, 0xbfb8aa3b, v33
	v_exp_f32_e32 v22, v22
	v_rcp_f32_e32 v31, v20
	v_add_f32_e32 v20, 1.0, v21
	v_rcp_f32_e32 v32, v20
	v_add_f32_e32 v20, 1.0, v22
	v_rcp_f32_e32 v33, v20

.LBB0_297:
	s_nop 0
	v_cvt_pk_bf16_f32 v6, v6, v7
	v_cvt_pk_bf16_f32 v7, v8, v9
	v_cvt_pk_bf16_f32 v8, v2, v3
	s_mul_i32 s98, s85, 176
	s_mov_b32 s99, 0
	v_lshl_add_u64 v[2:3], v[122:123], 0, s[98:99]
	s_and_b64 vcc, exec, s[4:5]
	v_cvt_pk_bf16_f32 v9, v4, v5
	global_store_dwordx4 v[2:3], v[6:9], off
	s_cbranch_vccnz .LBB0_299
	v_mul_f32_e32 v4, 0xbfb8aa3b, v10
	v_exp_f32_e32 v4, v4
	v_mul_f32_e32 v5, 0xbfb8aa3b, v11
	v_exp_f32_e32 v5, v5
	v_mul_f32_e32 v6, 0xbfb8aa3b, v13
	v_add_f32_e32 v4, 1.0, v4
	v_rcp_f32_e32 v10, v4
	v_mul_f32_e32 v4, 0xbfb8aa3b, v12
	v_exp_f32_e32 v4, v4
	v_exp_f32_e32 v6, v6
	v_add_f32_e32 v5, 1.0, v5
	v_rcp_f32_e32 v11, v5
	v_add_f32_e32 v4, 1.0, v4
	v_mul_f32_e32 v5, 0xbfb8aa3b, v14
	v_rcp_f32_e32 v12, v4
	v_add_f32_e32 v4, 1.0, v6
	v_exp_f32_e32 v5, v5
	v_mul_f32_e32 v6, 0xbfb8aa3b, v15
	v_exp_f32_e32 v6, v6
	v_rcp_f32_e32 v13, v4
	v_add_f32_e32 v4, 1.0, v5
	v_mul_f32_e32 v5, 0xbfb8aa3b, v16
	v_rcp_f32_e32 v14, v4
	v_add_f32_e32 v4, 1.0, v6
	v_exp_f32_e32 v5, v5
	v_mul_f32_e32 v6, 0xbfb8aa3b, v17
	v_exp_f32_e32 v6, v6
	v_rcp_f32_e32 v15, v4
	v_add_f32_e32 v4, 1.0, v5
	v_rcp_f32_e32 v16, v4
	v_add_f32_e32 v4, 1.0, v6
	v_rcp_f32_e32 v17, v4

.LBB0_1080:
	s_lshl_b32 s34, s7, 10
	s_ashr_i32 s35, s34, 31
	s_add_i32 s21, s34, 0x400
	v_mbcnt_lo_u32_b32 v144, -1, 0
	v_mbcnt_hi_u32_b32 v144, -1, v144
	s_cmp_eq_u32 s7, 2
	s_cselect_b64 s[30:31], -1, 0
	s_and_b64 s[36:37], s[30:31], exec
	v_and_or_b32 v145, v144, 15, s33
	v_ashrrev_i32_e32 v144, 1, v144
	s_cselect_b32 s36, 0x800, s21
	s_lshl_b32 s6, s6, 8
	v_and_b32_e32 v147, -8, v144
	v_lshl_add_u32 v146, s64, 8, v145
	v_mov_b64_e32 v[144:145], s[8:9]
	s_or_b32 s6, s6, s40
	v_mad_i64_i32 v[144:145], s[38:39], v146, s85, v[144:145]
	v_lshl_add_u64 v[150:151], v[144:145], 0, s[88:89]
	v_add_u32_e32 v144, s6, v147
	v_ashrrev_i32_e32 v145, 31, v144
	s_ashr_i32 s37, s36, 31
	v_lshl_add_u64 v[152:153], s[34:35], 1, v[150:151]
	v_lshlrev_b64 v[148:149], 1, v[144:145]
	v_lshl_add_u64 v[150:151], s[36:37], 1, v[150:151]
	v_lshl_add_u64 v[152:153], v[152:153], 0, v[148:149]
	v_lshl_add_u64 v[154:155], v[150:151], 0, v[148:149]
	s_cmp_lg_u64 s[30:31], 0
	s_cbranch_scc1 .Lmrg_fin_A
	global_load_dwordx4 v[158:161], v[152:153], off
	global_load_dwordx4 v[162:165], v[154:155], off
	global_load_dwordx4 v[176:179], v[152:153], off offset:256
	global_load_dwordx4 v[180:183], v[154:155], off offset:256
	s_waitcnt vmcnt(2)
	v_lshlrev_b32_e32 v147, 16, v158
	v_and_b32_e32 v166, 0xffff0000, v158
	v_lshlrev_b32_e32 v167, 16, v159
	v_and_b32_e32 v168, 0xffff0000, v159
	v_lshlrev_b32_e32 v158, 16, v162
	v_and_b32_e32 v159, 0xffff0000, v162
	v_lshlrev_b32_e32 v162, 16, v163
	v_and_b32_e32 v163, 0xffff0000, v163
	v_lshlrev_b32_e32 v169, 16, v160
	v_and_b32_e32 v170, 0xffff0000, v160
	v_lshlrev_b32_e32 v171, 16, v161
	v_and_b32_e32 v172, 0xffff0000, v161
	v_lshlrev_b32_e32 v160, 16, v164
	v_and_b32_e32 v161, 0xffff0000, v164
	v_lshlrev_b32_e32 v164, 16, v165
	v_and_b32_e32 v165, 0xffff0000, v165
	v_max_f32_e32 v158, 0x1e3ce508, v158
	v_max_f32_e32 v159, 0x1e3ce508, v159
	v_max_f32_e32 v162, 0x1e3ce508, v162
	v_max_f32_e32 v163, 0x1e3ce508, v163
	v_max_f32_e32 v160, 0x1e3ce508, v160
	v_max_f32_e32 v161, 0x1e3ce508, v161
	v_max_f32_e32 v164, 0x1e3ce508, v164
	v_max_f32_e32 v165, 0x1e3ce508, v165
	v_rcp_f32_e32 v158, v158
	v_rcp_f32_e32 v159, v159
	v_rcp_f32_e32 v162, v162
	v_rcp_f32_e32 v163, v163
	v_rcp_f32_e32 v160, v160
	v_rcp_f32_e32 v161, v161
	v_rcp_f32_e32 v164, v164
	v_rcp_f32_e32 v165, v165
	v_mov_b32_e32 v173, v160
	v_mov_b32_e32 v174, v161
	v_mul_f32_e32 v158, v158, v147
	v_mul_f32_e32 v159, v159, v166
	v_mul_f32_e32 v160, v162, v167
	v_mul_f32_e32 v161, v163, v168
	v_mul_f32_e32 v162, v173, v169
	v_mul_f32_e32 v163, v174, v170
	v_mul_f32_e32 v164, v164, v171
	v_mul_f32_e32 v165, v165, v172
	v_pk_mul_f32 v[112:113], v[112:113], v[160:161]
	v_pk_mul_f32 v[110:111], v[110:111], v[158:159]
	v_pk_mul_f32 v[108:109], v[108:109], v[164:165]
	v_pk_mul_f32 v[106:107], v[106:107], v[162:163]
	s_waitcnt vmcnt(0)
	v_cndmask_b32_e64 v147, 0, 1, s[30:31]
	v_cmp_ne_u32_e64 s[6:7], 1, v147
	v_lshlrev_b32_e32 v147, 16, v176
	v_lshlrev_b32_e32 v163, 16, v180
	v_and_b32_e32 v180, 0xffff0000, v180
	v_lshlrev_b32_e32 v164, 16, v181
	v_and_b32_e32 v181, 0xffff0000, v181
	v_lshlrev_b32_e32 v167, 16, v182
	v_and_b32_e32 v182, 0xffff0000, v182
	v_lshlrev_b32_e32 v168, 16, v183
	v_and_b32_e32 v183, 0xffff0000, v183
	v_max_f32_e32 v163, 0x1e3ce508, v163
	v_max_f32_e32 v180, 0x1e3ce508, v180
	v_max_f32_e32 v164, 0x1e3ce508, v164
	v_max_f32_e32 v181, 0x1e3ce508, v181
	v_max_f32_e32 v167, 0x1e3ce508, v167
	v_max_f32_e32 v182, 0x1e3ce508, v182
	v_max_f32_e32 v168, 0x1e3ce508, v168
	v_max_f32_e32 v183, 0x1e3ce508, v183
	v_rcp_f32_e32 v163, v163
	v_rcp_f32_e32 v180, v180
	v_rcp_f32_e32 v164, v164
	v_rcp_f32_e32 v181, v181
	v_rcp_f32_e32 v167, v167
	v_rcp_f32_e32 v182, v182
	v_rcp_f32_e32 v168, v168
	v_rcp_f32_e32 v183, v183
	v_and_b32_e32 v176, 0xffff0000, v176
	v_lshlrev_b32_e32 v162, 16, v177
	v_and_b32_e32 v177, 0xffff0000, v177
	v_lshlrev_b32_e32 v165, 16, v178
	v_and_b32_e32 v178, 0xffff0000, v178
	v_lshlrev_b32_e32 v166, 16, v179
	v_and_b32_e32 v179, 0xffff0000, v179
	v_mov_b32_e32 v169, v180
	v_mov_b32_e32 v170, v181
	v_mov_b32_e32 v171, v182
	v_mov_b32_e32 v172, v183
	v_mul_f32_e32 v180, v163, v147
	v_mul_f32_e32 v181, v169, v176
	v_mul_f32_e32 v182, v164, v162
	v_mul_f32_e32 v183, v170, v177
	v_mul_f32_e32 v176, v167, v165
	v_mul_f32_e32 v177, v171, v178
	v_mul_f32_e32 v178, v168, v166
	v_mul_f32_e32 v179, v172, v179
	v_pk_mul_f32 v[80:81], v[80:81], v[182:183]
	v_pk_mul_f32 v[78:79], v[78:79], v[180:181]
	v_pk_mul_f32 v[76:77], v[76:77], v[178:179]
	v_pk_mul_f32 v[74:75], v[74:75], v[176:177]
	v_or_b32_e32 v150, 16, v146
	s_nop 0
	v_mov_b64_e32 v[152:153], s[8:9]
	v_mad_i64_i32 v[152:153], s[38:39], v150, s85, v[152:153]
	v_lshl_add_u64 v[154:155], v[152:153], 0, s[88:89]
	v_lshl_add_u64 v[152:153], s[34:35], 1, v[154:155]
	v_lshl_add_u64 v[154:155], s[36:37], 1, v[154:155]
	v_lshl_add_u64 v[152:153], v[152:153], 0, v[148:149]
	v_lshl_add_u64 v[154:155], v[154:155], 0, v[148:149]
	global_load_dwordx4 v[158:161], v[152:153], off
	global_load_dwordx4 v[162:165], v[154:155], off
	global_load_dwordx4 v[176:179], v[152:153], off offset:256
	global_load_dwordx4 v[180:183], v[154:155], off offset:256
	s_waitcnt vmcnt(3)
	v_lshlrev_b32_e32 v147, 16, v158
	v_and_b32_e32 v166, 0xffff0000, v158
	v_lshlrev_b32_e32 v167, 16, v159
	v_and_b32_e32 v168, 0xffff0000, v159
	s_waitcnt vmcnt(2)
	v_lshlrev_b32_e32 v158, 16, v162
	v_and_b32_e32 v159, 0xffff0000, v162
	v_lshlrev_b32_e32 v162, 16, v163
	v_and_b32_e32 v163, 0xffff0000, v163
	v_lshlrev_b32_e32 v169, 16, v160
	v_and_b32_e32 v170, 0xffff0000, v160
	v_lshlrev_b32_e32 v171, 16, v161
	v_and_b32_e32 v172, 0xffff0000, v161
	v_lshlrev_b32_e32 v160, 16, v164
	v_and_b32_e32 v161, 0xffff0000, v164
	v_lshlrev_b32_e32 v164, 16, v165
	v_and_b32_e32 v165, 0xffff0000, v165
	v_max_f32_e32 v158, 0x1e3ce508, v158
	v_max_f32_e32 v159, 0x1e3ce508, v159
	v_max_f32_e32 v162, 0x1e3ce508, v162
	v_max_f32_e32 v163, 0x1e3ce508, v163
	v_max_f32_e32 v160, 0x1e3ce508, v160
	v_max_f32_e32 v161, 0x1e3ce508, v161
	v_max_f32_e32 v164, 0x1e3ce508, v164
	v_max_f32_e32 v165, 0x1e3ce508, v165
	v_rcp_f32_e32 v158, v158
	v_rcp_f32_e32 v159, v159
	v_rcp_f32_e32 v162, v162
	v_rcp_f32_e32 v163, v163
	v_rcp_f32_e32 v160, v160
	v_rcp_f32_e32 v161, v161
	v_rcp_f32_e32 v164, v164
	v_rcp_f32_e32 v165, v165
	v_mov_b32_e32 v173, v160
	v_mov_b32_e32 v174, v161
	v_mul_f32_e32 v158, v158, v147
	v_mul_f32_e32 v159, v159, v166
	v_mul_f32_e32 v160, v162, v167
	v_mul_f32_e32 v161, v163, v168
	v_mul_f32_e32 v162, v173, v169
	v_mul_f32_e32 v163, v174, v170
	v_mul_f32_e32 v164, v164, v171
	v_mul_f32_e32 v165, v165, v172
	v_pk_mul_f32 v[104:105], v[104:105], v[160:161]
	v_pk_mul_f32 v[102:103], v[102:103], v[158:159]
	v_pk_mul_f32 v[100:101], v[100:101], v[164:165]
	v_pk_mul_f32 v[98:99], v[98:99], v[162:163]
	s_waitcnt vmcnt(0)
	v_lshlrev_b32_e32 v147, 16, v176
	v_lshlrev_b32_e32 v163, 16, v180
	v_and_b32_e32 v180, 0xffff0000, v180
	v_lshlrev_b32_e32 v164, 16, v181
	v_and_b32_e32 v181, 0xffff0000, v181
	v_lshlrev_b32_e32 v167, 16, v182
	v_and_b32_e32 v182, 0xffff0000, v182
	v_lshlrev_b32_e32 v168, 16, v183
	v_and_b32_e32 v183, 0xffff0000, v183
	v_max_f32_e32 v163, 0x1e3ce508, v163
	v_max_f32_e32 v180, 0x1e3ce508, v180
	v_max_f32_e32 v164, 0x1e3ce508, v164
	v_max_f32_e32 v181, 0x1e3ce508, v181
	v_max_f32_e32 v167, 0x1e3ce508, v167
	v_max_f32_e32 v182, 0x1e3ce508, v182
	v_max_f32_e32 v168, 0x1e3ce508, v168
	v_max_f32_e32 v183, 0x1e3ce508, v183
	v_rcp_f32_e32 v163, v163
	v_rcp_f32_e32 v180, v180
	v_rcp_f32_e32 v164, v164
	v_rcp_f32_e32 v181, v181
	v_rcp_f32_e32 v167, v167
	v_rcp_f32_e32 v182, v182
	v_rcp_f32_e32 v168, v168
	v_rcp_f32_e32 v183, v183
	v_and_b32_e32 v176, 0xffff0000, v176
	v_lshlrev_b32_e32 v162, 16, v177
	v_and_b32_e32 v177, 0xffff0000, v177
	v_lshlrev_b32_e32 v165, 16, v178
	v_and_b32_e32 v178, 0xffff0000, v178
	v_lshlrev_b32_e32 v166, 16, v179
	v_and_b32_e32 v179, 0xffff0000, v179
	v_mov_b32_e32 v169, v180
	v_mov_b32_e32 v170, v181
	v_mov_b32_e32 v171, v182
	v_mov_b32_e32 v172, v183
	v_mul_f32_e32 v180, v163, v147
	v_mul_f32_e32 v181, v169, v176
	v_mul_f32_e32 v182, v164, v162
	v_mul_f32_e32 v183, v170, v177
	v_mul_f32_e32 v176, v167, v165
	v_mul_f32_e32 v177, v171, v178
	v_mul_f32_e32 v178, v168, v166
	v_mul_f32_e32 v179, v172, v179
	v_pk_mul_f32 v[72:73], v[72:73], v[182:183]
	v_pk_mul_f32 v[70:71], v[70:71], v[180:181]
	v_pk_mul_f32 v[68:69], v[68:69], v[178:179]
	v_pk_mul_f32 v[66:67], v[66:67], v[176:177]
	v_or_b32_e32 v150, 32, v146
	s_nop 0
	v_mov_b64_e32 v[152:153], s[8:9]
	v_mad_i64_i32 v[152:153], s[38:39], v150, s85, v[152:153]
	v_lshl_add_u64 v[154:155], v[152:153], 0, s[88:89]
	v_lshl_add_u64 v[152:153], s[34:35], 1, v[154:155]
	v_lshl_add_u64 v[154:155], s[36:37], 1, v[154:155]
	v_lshl_add_u64 v[152:153], v[152:153], 0, v[148:149]
	v_lshl_add_u64 v[154:155], v[154:155], 0, v[148:149]
	global_load_dwordx4 v[158:161], v[152:153], off
	global_load_dwordx4 v[162:165], v[154:155], off
	global_load_dwordx4 v[176:179], v[152:153], off offset:256
	global_load_dwordx4 v[180:183], v[154:155], off offset:256
	s_waitcnt vmcnt(3)
	v_lshlrev_b32_e32 v147, 16, v158
	v_and_b32_e32 v166, 0xffff0000, v158
	v_lshlrev_b32_e32 v167, 16, v159
	v_and_b32_e32 v168, 0xffff0000, v159
	s_waitcnt vmcnt(2)
	v_lshlrev_b32_e32 v158, 16, v162
	v_and_b32_e32 v159, 0xffff0000, v162
	v_lshlrev_b32_e32 v162, 16, v163
	v_and_b32_e32 v163, 0xffff0000, v163
	v_lshlrev_b32_e32 v169, 16, v160
	v_and_b32_e32 v170, 0xffff0000, v160
	v_lshlrev_b32_e32 v171, 16, v161
	v_and_b32_e32 v172, 0xffff0000, v161
	v_lshlrev_b32_e32 v160, 16, v164
	v_and_b32_e32 v161, 0xffff0000, v164
	v_lshlrev_b32_e32 v164, 16, v165
	v_and_b32_e32 v165, 0xffff0000, v165
	v_max_f32_e32 v158, 0x1e3ce508, v158
	v_max_f32_e32 v159, 0x1e3ce508, v159
	v_max_f32_e32 v162, 0x1e3ce508, v162
	v_max_f32_e32 v163, 0x1e3ce508, v163
	v_max_f32_e32 v160, 0x1e3ce508, v160
	v_max_f32_e32 v161, 0x1e3ce508, v161
	v_max_f32_e32 v164, 0x1e3ce508, v164
	v_max_f32_e32 v165, 0x1e3ce508, v165
	v_rcp_f32_e32 v158, v158
	v_rcp_f32_e32 v159, v159
	v_rcp_f32_e32 v162, v162
	v_rcp_f32_e32 v163, v163
	v_rcp_f32_e32 v160, v160
	v_rcp_f32_e32 v161, v161
	v_rcp_f32_e32 v164, v164
	v_rcp_f32_e32 v165, v165
	v_mov_b32_e32 v173, v160
	v_mov_b32_e32 v174, v161
	v_mul_f32_e32 v158, v158, v147
	v_mul_f32_e32 v159, v159, v166
	v_mul_f32_e32 v160, v162, v167
	v_mul_f32_e32 v161, v163, v168
	v_mul_f32_e32 v162, v173, v169
	v_mul_f32_e32 v163, v174, v170
	v_mul_f32_e32 v164, v164, v171
	v_mul_f32_e32 v165, v165, v172
	v_pk_mul_f32 v[96:97], v[96:97], v[160:161]
	v_pk_mul_f32 v[94:95], v[94:95], v[158:159]
	v_pk_mul_f32 v[92:93], v[92:93], v[164:165]
	v_pk_mul_f32 v[90:91], v[90:91], v[162:163]
	s_waitcnt vmcnt(0)
	v_lshlrev_b32_e32 v147, 16, v176
	v_lshlrev_b32_e32 v163, 16, v180
	v_and_b32_e32 v180, 0xffff0000, v180
	v_lshlrev_b32_e32 v164, 16, v181
	v_and_b32_e32 v181, 0xffff0000, v181
	v_lshlrev_b32_e32 v167, 16, v182
	v_and_b32_e32 v182, 0xffff0000, v182
	v_lshlrev_b32_e32 v168, 16, v183
	v_and_b32_e32 v183, 0xffff0000, v183
	v_max_f32_e32 v163, 0x1e3ce508, v163
	v_max_f32_e32 v180, 0x1e3ce508, v180
	v_max_f32_e32 v164, 0x1e3ce508, v164
	v_max_f32_e32 v181, 0x1e3ce508, v181
	v_max_f32_e32 v167, 0x1e3ce508, v167
	v_max_f32_e32 v182, 0x1e3ce508, v182
	v_max_f32_e32 v168, 0x1e3ce508, v168
	v_max_f32_e32 v183, 0x1e3ce508, v183
	v_rcp_f32_e32 v163, v163
	v_rcp_f32_e32 v180, v180
	v_rcp_f32_e32 v164, v164
	v_rcp_f32_e32 v181, v181
	v_rcp_f32_e32 v167, v167
	v_rcp_f32_e32 v182, v182
	v_rcp_f32_e32 v168, v168
	v_rcp_f32_e32 v183, v183
	v_and_b32_e32 v176, 0xffff0000, v176
	v_lshlrev_b32_e32 v162, 16, v177
	v_and_b32_e32 v177, 0xffff0000, v177
	v_lshlrev_b32_e32 v165, 16, v178
	v_and_b32_e32 v178, 0xffff0000, v178
	v_lshlrev_b32_e32 v166, 16, v179
	v_and_b32_e32 v179, 0xffff0000, v179
	v_mov_b32_e32 v169, v180
	v_mov_b32_e32 v170, v181
	v_mov_b32_e32 v171, v182
	v_mov_b32_e32 v172, v183
	v_mul_f32_e32 v180, v163, v147
	v_mul_f32_e32 v181, v169, v176
	v_mul_f32_e32 v182, v164, v162
	v_mul_f32_e32 v183, v170, v177
	v_mul_f32_e32 v176, v167, v165
	v_mul_f32_e32 v177, v171, v178
	v_mul_f32_e32 v178, v168, v166
	v_mul_f32_e32 v179, v172, v179
	v_pk_mul_f32 v[64:65], v[64:65], v[182:183]
	v_pk_mul_f32 v[62:63], v[62:63], v[180:181]
	v_pk_mul_f32 v[60:61], v[60:61], v[178:179]
	v_pk_mul_f32 v[58:59], v[58:59], v[176:177]
	v_or_b32_e32 v150, 48, v146
	s_nop 0
	v_mov_b64_e32 v[152:153], s[8:9]
	v_mad_i64_i32 v[152:153], s[38:39], v150, s85, v[152:153]
	v_lshl_add_u64 v[154:155], v[152:153], 0, s[88:89]
	v_lshl_add_u64 v[152:153], s[34:35], 1, v[154:155]
	v_lshl_add_u64 v[154:155], s[36:37], 1, v[154:155]
	v_lshl_add_u64 v[152:153], v[152:153], 0, v[148:149]
	v_lshl_add_u64 v[154:155], v[154:155], 0, v[148:149]
	global_load_dwordx4 v[158:161], v[152:153], off
	global_load_dwordx4 v[162:165], v[154:155], off
	global_load_dwordx4 v[176:179], v[152:153], off offset:256
	global_load_dwordx4 v[180:183], v[154:155], off offset:256
	s_waitcnt vmcnt(3)
	v_lshlrev_b32_e32 v147, 16, v158
	v_and_b32_e32 v166, 0xffff0000, v158
	v_lshlrev_b32_e32 v167, 16, v159
	v_and_b32_e32 v168, 0xffff0000, v159
	s_waitcnt vmcnt(2)
	v_lshlrev_b32_e32 v158, 16, v162
	v_and_b32_e32 v159, 0xffff0000, v162
	v_lshlrev_b32_e32 v162, 16, v163
	v_and_b32_e32 v163, 0xffff0000, v163
	v_lshlrev_b32_e32 v169, 16, v160
	v_and_b32_e32 v170, 0xffff0000, v160
	v_lshlrev_b32_e32 v171, 16, v161
	v_and_b32_e32 v172, 0xffff0000, v161
	v_lshlrev_b32_e32 v160, 16, v164
	v_and_b32_e32 v161, 0xffff0000, v164
	v_lshlrev_b32_e32 v164, 16, v165
	v_and_b32_e32 v165, 0xffff0000, v165
	v_max_f32_e32 v158, 0x1e3ce508, v158
	v_max_f32_e32 v159, 0x1e3ce508, v159
	v_max_f32_e32 v162, 0x1e3ce508, v162
	v_max_f32_e32 v163, 0x1e3ce508, v163
	v_max_f32_e32 v160, 0x1e3ce508, v160
	v_max_f32_e32 v161, 0x1e3ce508, v161
	v_max_f32_e32 v164, 0x1e3ce508, v164
	v_max_f32_e32 v165, 0x1e3ce508, v165
	v_rcp_f32_e32 v158, v158
	v_rcp_f32_e32 v159, v159
	v_rcp_f32_e32 v162, v162
	v_rcp_f32_e32 v163, v163
	v_rcp_f32_e32 v160, v160
	v_rcp_f32_e32 v161, v161
	v_rcp_f32_e32 v164, v164
	v_rcp_f32_e32 v165, v165
	v_mov_b32_e32 v173, v160
	v_mov_b32_e32 v174, v161
	v_mul_f32_e32 v158, v158, v147
	v_mul_f32_e32 v159, v159, v166
	v_mul_f32_e32 v160, v162, v167
	v_mul_f32_e32 v161, v163, v168
	v_mul_f32_e32 v162, v173, v169
	v_mul_f32_e32 v163, v174, v170
	v_mul_f32_e32 v164, v164, v171
	v_mul_f32_e32 v165, v165, v172
	v_pk_mul_f32 v[88:89], v[88:89], v[160:161]
	v_pk_mul_f32 v[86:87], v[86:87], v[158:159]
	v_pk_mul_f32 v[84:85], v[84:85], v[164:165]
	v_pk_mul_f32 v[82:83], v[82:83], v[162:163]
	s_waitcnt vmcnt(0)
	v_lshlrev_b32_e32 v147, 16, v176
	v_lshlrev_b32_e32 v163, 16, v180
	v_and_b32_e32 v180, 0xffff0000, v180
	v_lshlrev_b32_e32 v164, 16, v181
	v_and_b32_e32 v181, 0xffff0000, v181
	v_lshlrev_b32_e32 v167, 16, v182
	v_and_b32_e32 v182, 0xffff0000, v182
	v_lshlrev_b32_e32 v168, 16, v183
	v_and_b32_e32 v183, 0xffff0000, v183
	v_max_f32_e32 v163, 0x1e3ce508, v163
	v_max_f32_e32 v180, 0x1e3ce508, v180
	v_max_f32_e32 v164, 0x1e3ce508, v164
	v_max_f32_e32 v181, 0x1e3ce508, v181
	v_max_f32_e32 v167, 0x1e3ce508, v167
	v_max_f32_e32 v182, 0x1e3ce508, v182
	v_max_f32_e32 v168, 0x1e3ce508, v168
	v_max_f32_e32 v183, 0x1e3ce508, v183
	v_rcp_f32_e32 v163, v163
	v_rcp_f32_e32 v180, v180
	v_rcp_f32_e32 v164, v164
	v_rcp_f32_e32 v181, v181
	v_rcp_f32_e32 v167, v167
	v_rcp_f32_e32 v182, v182
	v_rcp_f32_e32 v168, v168
	v_rcp_f32_e32 v183, v183
	v_and_b32_e32 v176, 0xffff0000, v176
	v_lshlrev_b32_e32 v162, 16, v177
	v_and_b32_e32 v177, 0xffff0000, v177
	v_lshlrev_b32_e32 v165, 16, v178
	v_and_b32_e32 v178, 0xffff0000, v178
	v_lshlrev_b32_e32 v166, 16, v179
	v_and_b32_e32 v179, 0xffff0000, v179
	v_mov_b32_e32 v169, v180
	v_mov_b32_e32 v170, v181
	v_mov_b32_e32 v171, v182
	v_mov_b32_e32 v172, v183
	v_mul_f32_e32 v180, v163, v147
	v_mul_f32_e32 v181, v169, v176
	v_mul_f32_e32 v182, v164, v162
	v_mul_f32_e32 v183, v170, v177
	v_mul_f32_e32 v176, v167, v165
	v_mul_f32_e32 v177, v171, v178
	v_mul_f32_e32 v178, v168, v166
	v_mul_f32_e32 v179, v172, v179
	v_pk_mul_f32 v[56:57], v[56:57], v[182:183]
	v_pk_mul_f32 v[54:55], v[54:55], v[180:181]
	v_pk_mul_f32 v[52:53], v[52:53], v[178:179]
	v_pk_mul_f32 v[50:51], v[50:51], v[176:177]
	v_add_u32_e32 v150, 0x80, v146
	s_nop 0
	v_mov_b64_e32 v[152:153], s[8:9]
	v_mad_i64_i32 v[152:153], s[38:39], v150, s85, v[152:153]
	v_lshl_add_u64 v[154:155], v[152:153], 0, s[88:89]
	v_lshl_add_u64 v[152:153], s[34:35], 1, v[154:155]
	v_lshl_add_u64 v[154:155], s[36:37], 1, v[154:155]
	v_lshl_add_u64 v[152:153], v[152:153], 0, v[148:149]
	v_lshl_add_u64 v[154:155], v[154:155], 0, v[148:149]
	global_load_dwordx4 v[158:161], v[152:153], off
	global_load_dwordx4 v[162:165], v[154:155], off
	global_load_dwordx4 v[176:179], v[152:153], off offset:256
	global_load_dwordx4 v[180:183], v[154:155], off offset:256
	s_waitcnt vmcnt(3)
	v_lshlrev_b32_e32 v147, 16, v158
	v_and_b32_e32 v166, 0xffff0000, v158
	v_lshlrev_b32_e32 v167, 16, v159
	v_and_b32_e32 v168, 0xffff0000, v159
	s_waitcnt vmcnt(2)
	v_lshlrev_b32_e32 v158, 16, v162
	v_and_b32_e32 v159, 0xffff0000, v162
	v_lshlrev_b32_e32 v162, 16, v163
	v_and_b32_e32 v163, 0xffff0000, v163
	v_lshlrev_b32_e32 v169, 16, v160
	v_and_b32_e32 v170, 0xffff0000, v160
	v_lshlrev_b32_e32 v171, 16, v161
	v_and_b32_e32 v172, 0xffff0000, v161
	v_lshlrev_b32_e32 v160, 16, v164
	v_and_b32_e32 v161, 0xffff0000, v164
	v_lshlrev_b32_e32 v164, 16, v165
	v_and_b32_e32 v165, 0xffff0000, v165
	v_max_f32_e32 v158, 0x1e3ce508, v158
	v_max_f32_e32 v159, 0x1e3ce508, v159
	v_max_f32_e32 v162, 0x1e3ce508, v162
	v_max_f32_e32 v163, 0x1e3ce508, v163
	v_max_f32_e32 v160, 0x1e3ce508, v160
	v_max_f32_e32 v161, 0x1e3ce508, v161
	v_max_f32_e32 v164, 0x1e3ce508, v164
	v_max_f32_e32 v165, 0x1e3ce508, v165
	v_rcp_f32_e32 v158, v158
	v_rcp_f32_e32 v159, v159
	v_rcp_f32_e32 v162, v162
	v_rcp_f32_e32 v163, v163
	v_rcp_f32_e32 v160, v160
	v_rcp_f32_e32 v161, v161
	v_rcp_f32_e32 v164, v164
	v_rcp_f32_e32 v165, v165
	v_mov_b32_e32 v173, v160
	v_mov_b32_e32 v174, v161
	v_mul_f32_e32 v158, v158, v147
	v_mul_f32_e32 v159, v159, v166
	v_mul_f32_e32 v160, v162, v167
	v_mul_f32_e32 v161, v163, v168
	v_mul_f32_e32 v162, v173, v169
	v_mul_f32_e32 v163, v174, v170
	v_mul_f32_e32 v164, v164, v171
	v_mul_f32_e32 v165, v165, v172
	v_pk_mul_f32 v[48:49], v[48:49], v[160:161]
	v_pk_mul_f32 v[46:47], v[46:47], v[158:159]
	v_pk_mul_f32 v[44:45], v[44:45], v[164:165]
	v_pk_mul_f32 v[42:43], v[42:43], v[162:163]
	s_waitcnt vmcnt(0)
	v_lshlrev_b32_e32 v147, 16, v176
	v_lshlrev_b32_e32 v163, 16, v180
	v_and_b32_e32 v180, 0xffff0000, v180
	v_lshlrev_b32_e32 v164, 16, v181
	v_and_b32_e32 v181, 0xffff0000, v181
	v_lshlrev_b32_e32 v167, 16, v182
	v_and_b32_e32 v182, 0xffff0000, v182
	v_lshlrev_b32_e32 v168, 16, v183
	v_and_b32_e32 v183, 0xffff0000, v183
	v_max_f32_e32 v163, 0x1e3ce508, v163
	v_max_f32_e32 v180, 0x1e3ce508, v180
	v_max_f32_e32 v164, 0x1e3ce508, v164
	v_max_f32_e32 v181, 0x1e3ce508, v181
	v_max_f32_e32 v167, 0x1e3ce508, v167
	v_max_f32_e32 v182, 0x1e3ce508, v182
	v_max_f32_e32 v168, 0x1e3ce508, v168
	v_max_f32_e32 v183, 0x1e3ce508, v183
	v_rcp_f32_e32 v163, v163
	v_rcp_f32_e32 v180, v180
	v_rcp_f32_e32 v164, v164
	v_rcp_f32_e32 v181, v181
	v_rcp_f32_e32 v167, v167
	v_rcp_f32_e32 v182, v182
	v_rcp_f32_e32 v168, v168
	v_rcp_f32_e32 v183, v183
	v_and_b32_e32 v176, 0xffff0000, v176
	v_lshlrev_b32_e32 v162, 16, v177
	v_and_b32_e32 v177, 0xffff0000, v177
	v_lshlrev_b32_e32 v165, 16, v178
	v_and_b32_e32 v178, 0xffff0000, v178
	v_lshlrev_b32_e32 v166, 16, v179
	v_and_b32_e32 v179, 0xffff0000, v179
	v_mov_b32_e32 v169, v180
	v_mov_b32_e32 v170, v181
	v_mov_b32_e32 v171, v182
	v_mov_b32_e32 v172, v183
	v_mul_f32_e32 v180, v163, v147
	v_mul_f32_e32 v181, v169, v176
	v_mul_f32_e32 v182, v164, v162
	v_mul_f32_e32 v183, v170, v177
	v_mul_f32_e32 v176, v167, v165
	v_mul_f32_e32 v177, v171, v178
	v_mul_f32_e32 v178, v168, v166
	v_mul_f32_e32 v179, v172, v179
	v_pk_mul_f32 v[16:17], v[16:17], v[182:183]
	v_pk_mul_f32 v[14:15], v[14:15], v[180:181]
	v_pk_mul_f32 v[12:13], v[12:13], v[178:179]
	v_pk_mul_f32 v[10:11], v[10:11], v[176:177]
	v_add_u32_e32 v150, 0x90, v146
	s_nop 0
	v_mov_b64_e32 v[152:153], s[8:9]
	v_mad_i64_i32 v[152:153], s[38:39], v150, s85, v[152:153]
	v_lshl_add_u64 v[154:155], v[152:153], 0, s[88:89]
	v_lshl_add_u64 v[152:153], s[34:35], 1, v[154:155]
	v_lshl_add_u64 v[154:155], s[36:37], 1, v[154:155]
	v_lshl_add_u64 v[152:153], v[152:153], 0, v[148:149]
	v_lshl_add_u64 v[154:155], v[154:155], 0, v[148:149]
	global_load_dwordx4 v[158:161], v[152:153], off
	global_load_dwordx4 v[162:165], v[154:155], off
	global_load_dwordx4 v[176:179], v[152:153], off offset:256
	global_load_dwordx4 v[180:183], v[154:155], off offset:256
	s_waitcnt vmcnt(3)
	v_lshlrev_b32_e32 v147, 16, v158
	v_and_b32_e32 v166, 0xffff0000, v158
	v_lshlrev_b32_e32 v167, 16, v159
	v_and_b32_e32 v168, 0xffff0000, v159
	s_waitcnt vmcnt(2)
	v_lshlrev_b32_e32 v158, 16, v162
	v_and_b32_e32 v159, 0xffff0000, v162
	v_lshlrev_b32_e32 v162, 16, v163
	v_and_b32_e32 v163, 0xffff0000, v163
	v_lshlrev_b32_e32 v169, 16, v160
	v_and_b32_e32 v170, 0xffff0000, v160
	v_lshlrev_b32_e32 v171, 16, v161
	v_and_b32_e32 v172, 0xffff0000, v161
	v_lshlrev_b32_e32 v160, 16, v164
	v_and_b32_e32 v161, 0xffff0000, v164
	v_lshlrev_b32_e32 v164, 16, v165
	v_and_b32_e32 v165, 0xffff0000, v165
	v_max_f32_e32 v158, 0x1e3ce508, v158
	v_max_f32_e32 v159, 0x1e3ce508, v159
	v_max_f32_e32 v162, 0x1e3ce508, v162
	v_max_f32_e32 v163, 0x1e3ce508, v163
	v_max_f32_e32 v160, 0x1e3ce508, v160
	v_max_f32_e32 v161, 0x1e3ce508, v161
	v_max_f32_e32 v164, 0x1e3ce508, v164
	v_max_f32_e32 v165, 0x1e3ce508, v165
	v_rcp_f32_e32 v158, v158
	v_rcp_f32_e32 v159, v159
	v_rcp_f32_e32 v162, v162
	v_rcp_f32_e32 v163, v163
	v_rcp_f32_e32 v160, v160
	v_rcp_f32_e32 v161, v161
	v_rcp_f32_e32 v164, v164
	v_rcp_f32_e32 v165, v165
	v_mov_b32_e32 v173, v160
	v_mov_b32_e32 v174, v161
	v_mul_f32_e32 v158, v158, v147
	v_mul_f32_e32 v159, v159, v166
	v_mul_f32_e32 v160, v162, v167
	v_mul_f32_e32 v161, v163, v168
	v_mul_f32_e32 v162, v173, v169
	v_mul_f32_e32 v163, v174, v170
	v_mul_f32_e32 v164, v164, v171
	v_mul_f32_e32 v165, v165, v172
	v_pk_mul_f32 v[40:41], v[40:41], v[160:161]
	v_pk_mul_f32 v[38:39], v[38:39], v[158:159]
	v_pk_mul_f32 v[36:37], v[36:37], v[164:165]
	v_pk_mul_f32 v[34:35], v[34:35], v[162:163]
	s_waitcnt vmcnt(0)
	v_lshlrev_b32_e32 v147, 16, v176
	v_lshlrev_b32_e32 v163, 16, v180
	v_and_b32_e32 v180, 0xffff0000, v180
	v_lshlrev_b32_e32 v164, 16, v181
	v_and_b32_e32 v181, 0xffff0000, v181
	v_lshlrev_b32_e32 v167, 16, v182
	v_and_b32_e32 v182, 0xffff0000, v182
	v_lshlrev_b32_e32 v168, 16, v183
	v_and_b32_e32 v183, 0xffff0000, v183
	v_max_f32_e32 v163, 0x1e3ce508, v163
	v_max_f32_e32 v180, 0x1e3ce508, v180
	v_max_f32_e32 v164, 0x1e3ce508, v164
	v_max_f32_e32 v181, 0x1e3ce508, v181
	v_max_f32_e32 v167, 0x1e3ce508, v167
	v_max_f32_e32 v182, 0x1e3ce508, v182
	v_max_f32_e32 v168, 0x1e3ce508, v168
	v_max_f32_e32 v183, 0x1e3ce508, v183
	v_rcp_f32_e32 v163, v163
	v_rcp_f32_e32 v180, v180
	v_rcp_f32_e32 v164, v164
	v_rcp_f32_e32 v181, v181
	v_rcp_f32_e32 v167, v167
	v_rcp_f32_e32 v182, v182
	v_rcp_f32_e32 v168, v168
	v_rcp_f32_e32 v183, v183
	v_and_b32_e32 v176, 0xffff0000, v176
	v_lshlrev_b32_e32 v162, 16, v177
	v_and_b32_e32 v177, 0xffff0000, v177
	v_lshlrev_b32_e32 v165, 16, v178
	v_and_b32_e32 v178, 0xffff0000, v178
	v_lshlrev_b32_e32 v166, 16, v179
	v_and_b32_e32 v179, 0xffff0000, v179
	v_mov_b32_e32 v169, v180
	v_mov_b32_e32 v170, v181
	v_mov_b32_e32 v171, v182
	v_mov_b32_e32 v172, v183
	v_mul_f32_e32 v180, v163, v147
	v_mul_f32_e32 v181, v169, v176
	v_mul_f32_e32 v182, v164, v162
	v_mul_f32_e32 v183, v170, v177
	v_mul_f32_e32 v176, v167, v165
	v_mul_f32_e32 v177, v171, v178
	v_mul_f32_e32 v178, v168, v166
	v_mul_f32_e32 v179, v172, v179
	v_pk_mul_f32 v[8:9], v[8:9], v[182:183]
	v_pk_mul_f32 v[6:7], v[6:7], v[180:181]
	v_pk_mul_f32 v[4:5], v[4:5], v[178:179]
	v_pk_mul_f32 v[2:3], v[2:3], v[176:177]
	v_add_u32_e32 v150, 0xa0, v146
	s_nop 0
	v_mov_b64_e32 v[152:153], s[8:9]
	v_mad_i64_i32 v[152:153], s[38:39], v150, s85, v[152:153]
	v_lshl_add_u64 v[154:155], v[152:153], 0, s[88:89]
	v_lshl_add_u64 v[152:153], s[34:35], 1, v[154:155]
	v_lshl_add_u64 v[154:155], s[36:37], 1, v[154:155]
	v_lshl_add_u64 v[152:153], v[152:153], 0, v[148:149]
	v_lshl_add_u64 v[154:155], v[154:155], 0, v[148:149]
	global_load_dwordx4 v[158:161], v[152:153], off
	global_load_dwordx4 v[162:165], v[154:155], off
	global_load_dwordx4 v[176:179], v[152:153], off offset:256
	global_load_dwordx4 v[180:183], v[154:155], off offset:256
	s_waitcnt vmcnt(3)
	v_lshlrev_b32_e32 v147, 16, v158
	v_and_b32_e32 v166, 0xffff0000, v158
	v_lshlrev_b32_e32 v167, 16, v159
	v_and_b32_e32 v168, 0xffff0000, v159
	s_waitcnt vmcnt(2)
	v_lshlrev_b32_e32 v158, 16, v162
	v_and_b32_e32 v159, 0xffff0000, v162
	v_lshlrev_b32_e32 v162, 16, v163
	v_and_b32_e32 v163, 0xffff0000, v163
	v_lshlrev_b32_e32 v169, 16, v160
	v_and_b32_e32 v170, 0xffff0000, v160
	v_lshlrev_b32_e32 v171, 16, v161
	v_and_b32_e32 v172, 0xffff0000, v161
	v_lshlrev_b32_e32 v160, 16, v164
	v_and_b32_e32 v161, 0xffff0000, v164
	v_lshlrev_b32_e32 v164, 16, v165
	v_and_b32_e32 v165, 0xffff0000, v165
	v_max_f32_e32 v158, 0x1e3ce508, v158
	v_max_f32_e32 v159, 0x1e3ce508, v159
	v_max_f32_e32 v162, 0x1e3ce508, v162
	v_max_f32_e32 v163, 0x1e3ce508, v163
	v_max_f32_e32 v160, 0x1e3ce508, v160
	v_max_f32_e32 v161, 0x1e3ce508, v161
	v_max_f32_e32 v164, 0x1e3ce508, v164
	v_max_f32_e32 v165, 0x1e3ce508, v165
	v_rcp_f32_e32 v158, v158
	v_rcp_f32_e32 v159, v159
	v_rcp_f32_e32 v162, v162
	v_rcp_f32_e32 v163, v163
	v_rcp_f32_e32 v160, v160
	v_rcp_f32_e32 v161, v161
	v_rcp_f32_e32 v164, v164
	v_rcp_f32_e32 v165, v165
	v_mov_b32_e32 v173, v160
	v_mov_b32_e32 v174, v161
	v_mul_f32_e32 v158, v158, v147
	v_mul_f32_e32 v159, v159, v166
	v_mul_f32_e32 v160, v162, v167
	v_mul_f32_e32 v161, v163, v168
	v_mul_f32_e32 v162, v173, v169
	v_mul_f32_e32 v163, v174, v170
	v_mul_f32_e32 v164, v164, v171
	v_mul_f32_e32 v165, v165, v172
	v_pk_mul_f32 v[32:33], v[32:33], v[160:161]
	v_pk_mul_f32 v[30:31], v[30:31], v[158:159]
	v_pk_mul_f32 v[28:29], v[28:29], v[164:165]
	v_pk_mul_f32 v[26:27], v[26:27], v[162:163]
	s_waitcnt vmcnt(0)
	v_lshlrev_b32_e32 v147, 16, v176
	v_lshlrev_b32_e32 v163, 16, v180
	v_and_b32_e32 v180, 0xffff0000, v180
	v_lshlrev_b32_e32 v164, 16, v181
	v_and_b32_e32 v181, 0xffff0000, v181
	v_lshlrev_b32_e32 v167, 16, v182
	v_and_b32_e32 v182, 0xffff0000, v182
	v_lshlrev_b32_e32 v168, 16, v183
	v_and_b32_e32 v183, 0xffff0000, v183
	v_max_f32_e32 v163, 0x1e3ce508, v163
	v_max_f32_e32 v180, 0x1e3ce508, v180
	v_max_f32_e32 v164, 0x1e3ce508, v164
	v_max_f32_e32 v181, 0x1e3ce508, v181
	v_max_f32_e32 v167, 0x1e3ce508, v167
	v_max_f32_e32 v182, 0x1e3ce508, v182
	v_max_f32_e32 v168, 0x1e3ce508, v168
	v_max_f32_e32 v183, 0x1e3ce508, v183
	v_rcp_f32_e32 v163, v163
	v_rcp_f32_e32 v180, v180
	v_rcp_f32_e32 v164, v164
	v_rcp_f32_e32 v181, v181
	v_rcp_f32_e32 v167, v167
	v_rcp_f32_e32 v182, v182
	v_rcp_f32_e32 v168, v168
	v_rcp_f32_e32 v183, v183
	v_and_b32_e32 v176, 0xffff0000, v176
	v_lshlrev_b32_e32 v162, 16, v177
	v_and_b32_e32 v177, 0xffff0000, v177
	v_lshlrev_b32_e32 v165, 16, v178
	v_and_b32_e32 v178, 0xffff0000, v178
	v_lshlrev_b32_e32 v166, 16, v179
	v_and_b32_e32 v179, 0xffff0000, v179
	v_mov_b32_e32 v169, v180
	v_mov_b32_e32 v170, v181
	v_mov_b32_e32 v171, v182
	v_mov_b32_e32 v172, v183
	v_mul_f32_e32 v180, v163, v147
	v_mul_f32_e32 v181, v169, v176
	v_mul_f32_e32 v182, v164, v162
	v_mul_f32_e32 v183, v170, v177
	v_mul_f32_e32 v176, v167, v165
	v_mul_f32_e32 v177, v171, v178
	v_mul_f32_e32 v178, v168, v166
	v_mul_f32_e32 v179, v172, v179
	v_pk_mul_f32 v[116:117], v[116:117], v[182:183]
	v_pk_mul_f32 v[114:115], v[114:115], v[180:181]
	v_pk_mul_f32 v[120:121], v[120:121], v[178:179]
	v_pk_mul_f32 v[118:119], v[118:119], v[176:177]
	v_add_u32_e32 v146, 0xb0, v146
	v_mov_b64_e32 v[150:151], s[8:9]
	v_mad_i64_i32 v[150:151], s[38:39], v146, s85, v[150:151]
	v_lshl_add_u64 v[158:159], v[150:151], 0, s[88:89]
	v_lshl_add_u64 v[150:151], s[34:35], 1, v[158:159]
	v_lshl_add_u64 v[158:159], s[36:37], 1, v[158:159]
	v_lshl_add_u64 v[150:151], v[150:151], 0, v[148:149]
	v_lshl_add_u64 v[148:149], v[158:159], 0, v[148:149]
	global_load_dwordx4 v[152:155], v[150:151], off
	global_load_dwordx4 v[158:161], v[148:149], off
	v_ashrrev_i32_e32 v147, 31, v146
	v_lshlrev_b64 v[146:147], 11, v[146:147]
	v_lshl_add_u64 v[146:147], s[10:11], 0, v[146:147]
	s_waitcnt vmcnt(1)
	v_lshlrev_b32_e32 v162, 16, v152
	v_and_b32_e32 v163, 0xffff0000, v152
	v_lshlrev_b32_e32 v164, 16, v153
	v_and_b32_e32 v165, 0xffff0000, v153
	s_waitcnt vmcnt(0)
	v_lshlrev_b32_e32 v152, 16, v158
	v_and_b32_e32 v153, 0xffff0000, v158
	v_lshlrev_b32_e32 v158, 16, v159
	v_and_b32_e32 v159, 0xffff0000, v159
	v_lshlrev_b32_e32 v166, 16, v154
	v_and_b32_e32 v167, 0xffff0000, v154
	v_lshlrev_b32_e32 v168, 16, v155
	v_and_b32_e32 v169, 0xffff0000, v155
	v_lshlrev_b32_e32 v154, 16, v160
	v_and_b32_e32 v155, 0xffff0000, v160
	v_lshlrev_b32_e32 v160, 16, v161
	v_and_b32_e32 v161, 0xffff0000, v161
	v_max_f32_e32 v152, 0x1e3ce508, v152
	v_max_f32_e32 v153, 0x1e3ce508, v153
	v_max_f32_e32 v158, 0x1e3ce508, v158
	v_max_f32_e32 v159, 0x1e3ce508, v159
	v_max_f32_e32 v154, 0x1e3ce508, v154
	v_max_f32_e32 v155, 0x1e3ce508, v155
	v_max_f32_e32 v160, 0x1e3ce508, v160
	v_max_f32_e32 v161, 0x1e3ce508, v161
	v_rcp_f32_e32 v152, v152
	v_rcp_f32_e32 v153, v153
	v_rcp_f32_e32 v158, v158
	v_rcp_f32_e32 v159, v159
	v_rcp_f32_e32 v154, v154
	v_rcp_f32_e32 v155, v155
	v_rcp_f32_e32 v160, v160
	v_rcp_f32_e32 v161, v161
	v_mov_b32_e32 v170, v154
	v_mov_b32_e32 v171, v155
	v_mul_f32_e32 v152, v152, v162
	v_mul_f32_e32 v153, v153, v163
	v_mul_f32_e32 v154, v158, v164
	v_mul_f32_e32 v155, v159, v165
	v_mul_f32_e32 v158, v170, v166
	v_mul_f32_e32 v159, v171, v167
	v_mul_f32_e32 v160, v160, v168
	v_mul_f32_e32 v161, v161, v169
	v_pk_mul_f32 v[24:25], v[24:25], v[154:155]
	v_pk_mul_f32 v[22:23], v[22:23], v[152:153]
	v_pk_mul_f32 v[20:21], v[20:21], v[160:161]
	v_pk_mul_f32 v[18:19], v[18:19], v[158:159]
	global_load_dwordx4 v[150:153], v[150:151], off offset:256
	s_nop 0
	global_load_dwordx4 v[158:161], v[148:149], off offset:256
	s_waitcnt vmcnt(1)
	v_lshlrev_b32_e32 v162, 16, v152
	s_waitcnt vmcnt(0)
	v_lshlrev_b32_e32 v154, 16, v158
	v_and_b32_e32 v155, 0xffff0000, v158
	v_lshlrev_b32_e32 v158, 16, v159
	v_and_b32_e32 v159, 0xffff0000, v159
	v_and_b32_e32 v163, 0xffff0000, v152
	v_lshlrev_b32_e32 v164, 16, v153
	v_and_b32_e32 v165, 0xffff0000, v153
	v_lshlrev_b32_e32 v152, 16, v160
	v_and_b32_e32 v153, 0xffff0000, v160
	v_lshlrev_b32_e32 v160, 16, v161
	v_and_b32_e32 v161, 0xffff0000, v161
	v_max_f32_e32 v154, 0x1e3ce508, v154
	v_max_f32_e32 v155, 0x1e3ce508, v155
	v_max_f32_e32 v158, 0x1e3ce508, v158
	v_max_f32_e32 v159, 0x1e3ce508, v159
	v_max_f32_e32 v152, 0x1e3ce508, v152
	v_max_f32_e32 v153, 0x1e3ce508, v153
	v_max_f32_e32 v160, 0x1e3ce508, v160
	v_max_f32_e32 v161, 0x1e3ce508, v161
	v_rcp_f32_e32 v154, v154
	v_rcp_f32_e32 v155, v155
	v_rcp_f32_e32 v158, v158
	v_rcp_f32_e32 v159, v159
	v_rcp_f32_e32 v152, v152
	v_rcp_f32_e32 v153, v153
	v_rcp_f32_e32 v160, v160
	v_rcp_f32_e32 v161, v161
	v_lshlrev_b32_e32 v148, 16, v150
	v_and_b32_e32 v149, 0xffff0000, v150
	v_lshlrev_b32_e32 v150, 16, v151
	v_and_b32_e32 v151, 0xffff0000, v151
	v_mul_f32_e32 v148, v154, v148
	v_mul_f32_e32 v149, v155, v149
	v_mul_f32_e32 v150, v158, v150
	v_mul_f32_e32 v151, v159, v151
	v_mul_f32_e32 v152, v152, v162
	v_mul_f32_e32 v153, v153, v163
	v_mul_f32_e32 v154, v160, v164
	v_mul_f32_e32 v155, v161, v165
	v_pk_mul_f32 v[124:125], v[124:125], v[150:151]
	v_pk_mul_f32 v[122:123], v[122:123], v[148:149]
	v_pk_mul_f32 v[128:129], v[128:129], v[154:155]
	v_pk_mul_f32 v[126:127], v[126:127], v[152:153]
	s_branch .LBB0_1112

.Ltks_item:
	s_cmp_ge_i32 s24, s25
	s_cbranch_scc1 .Ltks_done
	s_cmp_lt_i32 s24, 0x100
	s_movk_i32 s26, 0x800
	s_cselect_b32 s26, s26, 0x100
	s_cselect_b32 s27, 64, 8
	s_cselect_b32 s31, 0, 0x100
	s_sub_i32 s31, s24, s31
	s_lshr_b32 s33, s31, 4
	s_and_b32 s30, s31, 15
	s_lshl_b32 s28, s33, 11
	s_lshl_b32 s29, s33, 8
	s_lshl_b32 s31, s33, 5
	s_addk_i32 s31, 0x1000
	s_add_i32 s33, s29, 0x8000
	s_cmp_lt_i32 s24, 0x100
	s_cselect_b32 s28, s28, s33
	s_cselect_b32 s29, s29, s31
	s_lshl_b32 s33, s28, 4
	s_add_i32 s33, s33, s30
	s_lshl_b32 s33, s33, 2
	s_add_u32 s98, s34, 0x400000
	s_addc_u32 s99, s35, 0
	s_add_i32 s31, s26, -1
	v_lshl_add_u32 v206, v18, 2, 0
	v_lshl_add_u32 v207, v18, 2, 1
	v_lshl_add_u32 v208, v18, 2, 2
	v_lshl_add_u32 v209, v18, 2, 3
	v_min_u32_e32 v210, s31, v206
	v_min_u32_e32 v211, s31, v207
	v_min_u32_e32 v212, s31, v208
	v_min_u32_e32 v213, s31, v209
	v_lshl_add_u32 v210, v210, 6, s33
	v_lshl_add_u32 v211, v211, 6, s33
	v_lshl_add_u32 v212, v212, 6, s33
	v_lshl_add_u32 v213, v213, 6, s33
	global_load_dword v3, v210, s[98:99]
	global_load_dword v5, v211, s[98:99]
	global_load_dword v7, v212, s[98:99]
	global_load_dword v9, v213, s[98:99]
	v_cmp_gt_u32_e64 s[14:15], s26, v206
	v_not_b32_e32 v2, v206
	v_cmp_gt_u32_e64 s[16:17], s26, v207
	v_not_b32_e32 v4, v207
	v_cmp_gt_u32_e64 s[18:19], s26, v208
	v_not_b32_e32 v6, v208
	v_cmp_gt_u32_e64 s[20:21], s26, v209
	v_not_b32_e32 v8, v209
	v_cndmask_b32_e64 v2, 0, v2, s[14:15]
	v_cndmask_b32_e64 v4, 0, v4, s[16:17]
	v_cndmask_b32_e64 v6, 0, v6, s[18:19]
	v_cndmask_b32_e64 v8, 0, v8, s[20:21]
	s_waitcnt vmcnt(0)
	v_cndmask_b32_e64 v3, 0, v3, s[14:15]
	v_cndmask_b32_e64 v5, 0, v5, s[16:17]
	v_cndmask_b32_e64 v7, 0, v7, s[18:19]
	v_cndmask_b32_e64 v9, 0, v9, s[20:21]
	v_cmp_lt_u64_e64 s[14:15], v[2:3], v[4:5]
	v_cmp_gt_u64_e64 s[16:17], v[6:7], v[8:9]
	s_nop 1
	v_cndmask_b32_e64 v188, v2, v4, s[14:15]
	v_cndmask_b32_e64 v189, v3, v5, s[14:15]
	v_cndmask_b32_e64 v190, v4, v2, s[14:15]
	v_cndmask_b32_e64 v191, v5, v3, s[14:15]
	v_cndmask_b32_e64 v192, v6, v8, s[16:17]
	v_cndmask_b32_e64 v193, v7, v9, s[16:17]
	v_cndmask_b32_e64 v194, v8, v6, s[16:17]
	v_cndmask_b32_e64 v195, v9, v7, s[16:17]
	s_not_b64 s[12:13], s[0:1]
	v_cmp_gt_u64_e64 s[14:15], v[188:189], v[192:193]
	v_cmp_gt_u64_e64 s[16:17], v[190:191], v[194:195]
	s_xor_b64 s[14:15], s[14:15], s[12:13]
	s_xor_b64 s[16:17], s[16:17], s[12:13]
	v_cndmask_b32_e64 v2, v188, v192, s[14:15]
	v_cndmask_b32_e64 v3, v189, v193, s[14:15]
	v_cndmask_b32_e64 v6, v192, v188, s[14:15]
	v_cndmask_b32_e64 v7, v193, v189, s[14:15]
	v_cndmask_b32_e64 v4, v190, v194, s[16:17]
	v_cndmask_b32_e64 v5, v191, v195, s[16:17]
	v_cndmask_b32_e64 v8, v194, v190, s[16:17]
	v_cndmask_b32_e64 v9, v195, v191, s[16:17]
	s_not_b64 s[12:13], s[0:1]
	v_cmp_gt_u64_e64 s[14:15], v[2:3], v[4:5]
	v_cmp_gt_u64_e64 s[16:17], v[6:7], v[8:9]
	s_xor_b64 s[14:15], s[14:15], s[12:13]
	s_xor_b64 s[16:17], s[16:17], s[12:13]
	v_cndmask_b32_e64 v188, v2, v4, s[14:15]
	v_cndmask_b32_e64 v189, v3, v5, s[14:15]
	v_cndmask_b32_e64 v190, v4, v2, s[14:15]
	v_cndmask_b32_e64 v191, v5, v3, s[14:15]
	v_cndmask_b32_e64 v192, v6, v8, s[16:17]
	v_cndmask_b32_e64 v193, v7, v9, s[16:17]
	v_cndmask_b32_e64 v194, v8, v6, s[16:17]
	v_cndmask_b32_e64 v195, v9, v7, s[16:17]
	s_xnor_b64 s[12:13], s[2:3], s[0:1]
	ds_bpermute_b32 v10, v196, v188
	ds_bpermute_b32 v11, v196, v189
	ds_bpermute_b32 v12, v196, v190
	ds_bpermute_b32 v13, v196, v191
	ds_bpermute_b32 v14, v196, v192
	ds_bpermute_b32 v15, v196, v193
	ds_bpermute_b32 v16, v196, v194
	ds_bpermute_b32 v17, v196, v195
	s_waitcnt lgkmcnt(6)
	v_cmp_gt_u64_e64 s[14:15], v[188:189], v[10:11]
	s_waitcnt lgkmcnt(4)
	v_cmp_gt_u64_e64 s[16:17], v[190:191], v[12:13]
	s_waitcnt lgkmcnt(2)
	v_cmp_gt_u64_e64 s[18:19], v[192:193], v[14:15]
	s_waitcnt lgkmcnt(0)
	v_cmp_gt_u64_e64 s[20:21], v[194:195], v[16:17]
	s_xor_b64 s[14:15], s[14:15], s[12:13]
	s_xor_b64 s[16:17], s[16:17], s[12:13]
	s_xor_b64 s[18:19], s[18:19], s[12:13]
	s_xor_b64 s[20:21], s[20:21], s[12:13]
	v_cndmask_b32_e64 v188, v188, v10, s[14:15]
	v_cndmask_b32_e64 v189, v189, v11, s[14:15]
	v_cndmask_b32_e64 v190, v190, v12, s[16:17]
	v_cndmask_b32_e64 v191, v191, v13, s[16:17]
	v_cndmask_b32_e64 v192, v192, v14, s[18:19]
	v_cndmask_b32_e64 v193, v193, v15, s[18:19]
	v_cndmask_b32_e64 v194, v194, v16, s[20:21]
	v_cndmask_b32_e64 v195, v195, v17, s[20:21]
	s_not_b64 s[12:13], s[2:3]
	v_cmp_gt_u64_e64 s[14:15], v[188:189], v[192:193]
	v_cmp_gt_u64_e64 s[16:17], v[190:191], v[194:195]
	s_xor_b64 s[14:15], s[14:15], s[12:13]
	s_xor_b64 s[16:17], s[16:17], s[12:13]
	v_cndmask_b32_e64 v2, v188, v192, s[14:15]
	v_cndmask_b32_e64 v3, v189, v193, s[14:15]
	v_cndmask_b32_e64 v6, v192, v188, s[14:15]
	v_cndmask_b32_e64 v7, v193, v189, s[14:15]
	v_cndmask_b32_e64 v4, v190, v194, s[16:17]
	v_cndmask_b32_e64 v5, v191, v195, s[16:17]
	v_cndmask_b32_e64 v8, v194, v190, s[16:17]
	v_cndmask_b32_e64 v9, v195, v191, s[16:17]
	s_not_b64 s[12:13], s[2:3]
	v_cmp_gt_u64_e64 s[14:15], v[2:3], v[4:5]
	v_cmp_gt_u64_e64 s[16:17], v[6:7], v[8:9]
	s_xor_b64 s[14:15], s[14:15], s[12:13]
	s_xor_b64 s[16:17], s[16:17], s[12:13]
	v_cndmask_b32_e64 v188, v2, v4, s[14:15]
	v_cndmask_b32_e64 v189, v3, v5, s[14:15]
	v_cndmask_b32_e64 v190, v4, v2, s[14:15]
	v_cndmask_b32_e64 v191, v5, v3, s[14:15]
	v_cndmask_b32_e64 v192, v6, v8, s[16:17]
	v_cndmask_b32_e64 v193, v7, v9, s[16:17]
	v_cndmask_b32_e64 v194, v8, v6, s[16:17]
	v_cndmask_b32_e64 v195, v9, v7, s[16:17]
	s_xnor_b64 s[12:13], s[4:5], s[2:3]
	ds_bpermute_b32 v10, v197, v188
	ds_bpermute_b32 v11, v197, v189
	ds_bpermute_b32 v12, v197, v190
	ds_bpermute_b32 v13, v197, v191
	ds_bpermute_b32 v14, v197, v192
	ds_bpermute_b32 v15, v197, v193
	ds_bpermute_b32 v16, v197, v194
	ds_bpermute_b32 v17, v197, v195
	s_waitcnt lgkmcnt(6)
	v_cmp_gt_u64_e64 s[14:15], v[188:189], v[10:11]
	s_waitcnt lgkmcnt(4)
	v_cmp_gt_u64_e64 s[16:17], v[190:191], v[12:13]
	s_waitcnt lgkmcnt(2)
	v_cmp_gt_u64_e64 s[18:19], v[192:193], v[14:15]
	s_waitcnt lgkmcnt(0)
	v_cmp_gt_u64_e64 s[20:21], v[194:195], v[16:17]
	s_xor_b64 s[14:15], s[14:15], s[12:13]
	s_xor_b64 s[16:17], s[16:17], s[12:13]
	s_xor_b64 s[18:19], s[18:19], s[12:13]
	s_xor_b64 s[20:21], s[20:21], s[12:13]
	v_cndmask_b32_e64 v188, v188, v10, s[14:15]
	v_cndmask_b32_e64 v189, v189, v11, s[14:15]
	v_cndmask_b32_e64 v190, v190, v12, s[16:17]
	v_cndmask_b32_e64 v191, v191, v13, s[16:17]
	v_cndmask_b32_e64 v192, v192, v14, s[18:19]
	v_cndmask_b32_e64 v193, v193, v15, s[18:19]
	v_cndmask_b32_e64 v194, v194, v16, s[20:21]
	v_cndmask_b32_e64 v195, v195, v17, s[20:21]
	s_xnor_b64 s[12:13], s[4:5], s[0:1]
	ds_bpermute_b32 v10, v196, v188
	ds_bpermute_b32 v11, v196, v189
	ds_bpermute_b32 v12, v196, v190
	ds_bpermute_b32 v13, v196, v191
	ds_bpermute_b32 v14, v196, v192
	ds_bpermute_b32 v15, v196, v193
	ds_bpermute_b32 v16, v196, v194
	ds_bpermute_b32 v17, v196, v195
	s_waitcnt lgkmcnt(6)
	v_cmp_gt_u64_e64 s[14:15], v[188:189], v[10:11]
	s_waitcnt lgkmcnt(4)
	v_cmp_gt_u64_e64 s[16:17], v[190:191], v[12:13]
	s_waitcnt lgkmcnt(2)
	v_cmp_gt_u64_e64 s[18:19], v[192:193], v[14:15]
	s_waitcnt lgkmcnt(0)
	v_cmp_gt_u64_e64 s[20:21], v[194:195], v[16:17]
	s_xor_b64 s[14:15], s[14:15], s[12:13]
	s_xor_b64 s[16:17], s[16:17], s[12:13]
	s_xor_b64 s[18:19], s[18:19], s[12:13]
	s_xor_b64 s[20:21], s[20:21], s[12:13]
	v_cndmask_b32_e64 v188, v188, v10, s[14:15]
	v_cndmask_b32_e64 v189, v189, v11, s[14:15]
	v_cndmask_b32_e64 v190, v190, v12, s[16:17]
	v_cndmask_b32_e64 v191, v191, v13, s[16:17]
	v_cndmask_b32_e64 v192, v192, v14, s[18:19]
	v_cndmask_b32_e64 v193, v193, v15, s[18:19]
	v_cndmask_b32_e64 v194, v194, v16, s[20:21]
	v_cndmask_b32_e64 v195, v195, v17, s[20:21]
	s_not_b64 s[12:13], s[4:5]
	v_cmp_gt_u64_e64 s[14:15], v[188:189], v[192:193]
	v_cmp_gt_u64_e64 s[16:17], v[190:191], v[194:195]
	s_xor_b64 s[14:15], s[14:15], s[12:13]
	s_xor_b64 s[16:17], s[16:17], s[12:13]
	v_cndmask_b32_e64 v2, v188, v192, s[14:15]
	v_cndmask_b32_e64 v3, v189, v193, s[14:15]
	v_cndmask_b32_e64 v6, v192, v188, s[14:15]
	v_cndmask_b32_e64 v7, v193, v189, s[14:15]
	v_cndmask_b32_e64 v4, v190, v194, s[16:17]
	v_cndmask_b32_e64 v5, v191, v195, s[16:17]
	v_cndmask_b32_e64 v8, v194, v190, s[16:17]
	v_cndmask_b32_e64 v9, v195, v191, s[16:17]
	s_not_b64 s[12:13], s[4:5]
	v_cmp_gt_u64_e64 s[14:15], v[2:3], v[4:5]
	v_cmp_gt_u64_e64 s[16:17], v[6:7], v[8:9]
	s_xor_b64 s[14:15], s[14:15], s[12:13]
	s_xor_b64 s[16:17], s[16:17], s[12:13]
	v_cndmask_b32_e64 v188, v2, v4, s[14:15]
	v_cndmask_b32_e64 v189, v3, v5, s[14:15]
	v_cndmask_b32_e64 v190, v4, v2, s[14:15]
	v_cndmask_b32_e64 v191, v5, v3, s[14:15]
	v_cndmask_b32_e64 v192, v6, v8, s[16:17]
	v_cndmask_b32_e64 v193, v7, v9, s[16:17]
	v_cndmask_b32_e64 v194, v8, v6, s[16:17]
	v_cndmask_b32_e64 v195, v9, v7, s[16:17]
	s_xnor_b64 s[12:13], s[6:7], s[4:5]
	ds_bpermute_b32 v10, v198, v188
	ds_bpermute_b32 v11, v198, v189
	ds_bpermute_b32 v12, v198, v190
	ds_bpermute_b32 v13, v198, v191
	ds_bpermute_b32 v14, v198, v192
	ds_bpermute_b32 v15, v198, v193
	ds_bpermute_b32 v16, v198, v194
	ds_bpermute_b32 v17, v198, v195
	s_waitcnt lgkmcnt(6)
	v_cmp_gt_u64_e64 s[14:15], v[188:189], v[10:11]
	s_waitcnt lgkmcnt(4)
	v_cmp_gt_u64_e64 s[16:17], v[190:191], v[12:13]
	s_waitcnt lgkmcnt(2)
	v_cmp_gt_u64_e64 s[18:19], v[192:193], v[14:15]
	s_waitcnt lgkmcnt(0)
	v_cmp_gt_u64_e64 s[20:21], v[194:195], v[16:17]
	s_xor_b64 s[14:15], s[14:15], s[12:13]
	s_xor_b64 s[16:17], s[16:17], s[12:13]
	s_xor_b64 s[18:19], s[18:19], s[12:13]
	s_xor_b64 s[20:21], s[20:21], s[12:13]
	v_cndmask_b32_e64 v188, v188, v10, s[14:15]
	v_cndmask_b32_e64 v189, v189, v11, s[14:15]
	v_cndmask_b32_e64 v190, v190, v12, s[16:17]
	v_cndmask_b32_e64 v191, v191, v13, s[16:17]
	v_cndmask_b32_e64 v192, v192, v14, s[18:19]
	v_cndmask_b32_e64 v193, v193, v15, s[18:19]
	v_cndmask_b32_e64 v194, v194, v16, s[20:21]
	v_cndmask_b32_e64 v195, v195, v17, s[20:21]
	s_xnor_b64 s[12:13], s[6:7], s[2:3]
	ds_bpermute_b32 v10, v197, v188
	ds_bpermute_b32 v11, v197, v189
	ds_bpermute_b32 v12, v197, v190
	ds_bpermute_b32 v13, v197, v191
	ds_bpermute_b32 v14, v197, v192
	ds_bpermute_b32 v15, v197, v193
	ds_bpermute_b32 v16, v197, v194
	ds_bpermute_b32 v17, v197, v195
	s_waitcnt lgkmcnt(6)
	v_cmp_gt_u64_e64 s[14:15], v[188:189], v[10:11]
	s_waitcnt lgkmcnt(4)
	v_cmp_gt_u64_e64 s[16:17], v[190:191], v[12:13]
	s_waitcnt lgkmcnt(2)
	v_cmp_gt_u64_e64 s[18:19], v[192:193], v[14:15]
	s_waitcnt lgkmcnt(0)
	v_cmp_gt_u64_e64 s[20:21], v[194:195], v[16:17]
	s_xor_b64 s[14:15], s[14:15], s[12:13]
	s_xor_b64 s[16:17], s[16:17], s[12:13]
	s_xor_b64 s[18:19], s[18:19], s[12:13]
	s_xor_b64 s[20:21], s[20:21], s[12:13]
	v_cndmask_b32_e64 v188, v188, v10, s[14:15]
	v_cndmask_b32_e64 v189, v189, v11, s[14:15]
	v_cndmask_b32_e64 v190, v190, v12, s[16:17]
	v_cndmask_b32_e64 v191, v191, v13, s[16:17]
	v_cndmask_b32_e64 v192, v192, v14, s[18:19]
	v_cndmask_b32_e64 v193, v193, v15, s[18:19]
	v_cndmask_b32_e64 v194, v194, v16, s[20:21]
	v_cndmask_b32_e64 v195, v195, v17, s[20:21]
	s_xnor_b64 s[12:13], s[6:7], s[0:1]
	ds_bpermute_b32 v10, v196, v188
	ds_bpermute_b32 v11, v196, v189
	ds_bpermute_b32 v12, v196, v190
	ds_bpermute_b32 v13, v196, v191
	ds_bpermute_b32 v14, v196, v192
	ds_bpermute_b32 v15, v196, v193
	ds_bpermute_b32 v16, v196, v194
	ds_bpermute_b32 v17, v196, v195
	s_waitcnt lgkmcnt(6)
	v_cmp_gt_u64_e64 s[14:15], v[188:189], v[10:11]
	s_waitcnt lgkmcnt(4)
	v_cmp_gt_u64_e64 s[16:17], v[190:191], v[12:13]
	s_waitcnt lgkmcnt(2)
	v_cmp_gt_u64_e64 s[18:19], v[192:193], v[14:15]
	s_waitcnt lgkmcnt(0)
	v_cmp_gt_u64_e64 s[20:21], v[194:195], v[16:17]
	s_xor_b64 s[14:15], s[14:15], s[12:13]
	s_xor_b64 s[16:17], s[16:17], s[12:13]
	s_xor_b64 s[18:19], s[18:19], s[12:13]
	s_xor_b64 s[20:21], s[20:21], s[12:13]
	v_cndmask_b32_e64 v188, v188, v10, s[14:15]
	v_cndmask_b32_e64 v189, v189, v11, s[14:15]
	v_cndmask_b32_e64 v190, v190, v12, s[16:17]
	v_cndmask_b32_e64 v191, v191, v13, s[16:17]
	v_cndmask_b32_e64 v192, v192, v14, s[18:19]
	v_cndmask_b32_e64 v193, v193, v15, s[18:19]
	v_cndmask_b32_e64 v194, v194, v16, s[20:21]
	v_cndmask_b32_e64 v195, v195, v17, s[20:21]
	s_not_b64 s[12:13], s[6:7]
	v_cmp_gt_u64_e64 s[14:15], v[188:189], v[192:193]
	v_cmp_gt_u64_e64 s[16:17], v[190:191], v[194:195]
	s_xor_b64 s[14:15], s[14:15], s[12:13]
	s_xor_b64 s[16:17], s[16:17], s[12:13]
	v_cndmask_b32_e64 v2, v188, v192, s[14:15]
	v_cndmask_b32_e64 v3, v189, v193, s[14:15]
	v_cndmask_b32_e64 v6, v192, v188, s[14:15]
	v_cndmask_b32_e64 v7, v193, v189, s[14:15]
	v_cndmask_b32_e64 v4, v190, v194, s[16:17]
	v_cndmask_b32_e64 v5, v191, v195, s[16:17]
	v_cndmask_b32_e64 v8, v194, v190, s[16:17]
	v_cndmask_b32_e64 v9, v195, v191, s[16:17]
	s_not_b64 s[12:13], s[6:7]
	v_cmp_gt_u64_e64 s[14:15], v[2:3], v[4:5]
	v_cmp_gt_u64_e64 s[16:17], v[6:7], v[8:9]
	s_xor_b64 s[14:15], s[14:15], s[12:13]
	s_xor_b64 s[16:17], s[16:17], s[12:13]
	v_cndmask_b32_e64 v188, v2, v4, s[14:15]
	v_cndmask_b32_e64 v189, v3, v5, s[14:15]
	v_cndmask_b32_e64 v190, v4, v2, s[14:15]
	v_cndmask_b32_e64 v191, v5, v3, s[14:15]
	v_cndmask_b32_e64 v192, v6, v8, s[16:17]
	v_cndmask_b32_e64 v193, v7, v9, s[16:17]
	v_cndmask_b32_e64 v194, v8, v6, s[16:17]
	v_cndmask_b32_e64 v195, v9, v7, s[16:17]
	s_xnor_b64 s[12:13], s[8:9], s[6:7]
	ds_bpermute_b32 v10, v199, v188
	ds_bpermute_b32 v11, v199, v189
	ds_bpermute_b32 v12, v199, v190
	ds_bpermute_b32 v13, v199, v191
	ds_bpermute_b32 v14, v199, v192
	ds_bpermute_b32 v15, v199, v193
	ds_bpermute_b32 v16, v199, v194
	ds_bpermute_b32 v17, v199, v195
	s_waitcnt lgkmcnt(6)
	v_cmp_gt_u64_e64 s[14:15], v[188:189], v[10:11]
	s_waitcnt lgkmcnt(4)
	v_cmp_gt_u64_e64 s[16:17], v[190:191], v[12:13]
	s_waitcnt lgkmcnt(2)
	v_cmp_gt_u64_e64 s[18:19], v[192:193], v[14:15]
	s_waitcnt lgkmcnt(0)
	v_cmp_gt_u64_e64 s[20:21], v[194:195], v[16:17]
	s_xor_b64 s[14:15], s[14:15], s[12:13]
	s_xor_b64 s[16:17], s[16:17], s[12:13]
	s_xor_b64 s[18:19], s[18:19], s[12:13]
	s_xor_b64 s[20:21], s[20:21], s[12:13]
	v_cndmask_b32_e64 v188, v188, v10, s[14:15]
	v_cndmask_b32_e64 v189, v189, v11, s[14:15]
	v_cndmask_b32_e64 v190, v190, v12, s[16:17]
	v_cndmask_b32_e64 v191, v191, v13, s[16:17]
	v_cndmask_b32_e64 v192, v192, v14, s[18:19]
	v_cndmask_b32_e64 v193, v193, v15, s[18:19]
	v_cndmask_b32_e64 v194, v194, v16, s[20:21]
	v_cndmask_b32_e64 v195, v195, v17, s[20:21]
	s_xnor_b64 s[12:13], s[8:9], s[4:5]
	ds_bpermute_b32 v10, v198, v188
	ds_bpermute_b32 v11, v198, v189
	ds_bpermute_b32 v12, v198, v190
	ds_bpermute_b32 v13, v198, v191
	ds_bpermute_b32 v14, v198, v192
	ds_bpermute_b32 v15, v198, v193
	ds_bpermute_b32 v16, v198, v194
	ds_bpermute_b32 v17, v198, v195
	s_waitcnt lgkmcnt(6)
	v_cmp_gt_u64_e64 s[14:15], v[188:189], v[10:11]
	s_waitcnt lgkmcnt(4)
	v_cmp_gt_u64_e64 s[16:17], v[190:191], v[12:13]
	s_waitcnt lgkmcnt(2)
	v_cmp_gt_u64_e64 s[18:19], v[192:193], v[14:15]
	s_waitcnt lgkmcnt(0)
	v_cmp_gt_u64_e64 s[20:21], v[194:195], v[16:17]
	s_xor_b64 s[14:15], s[14:15], s[12:13]
	s_xor_b64 s[16:17], s[16:17], s[12:13]
	s_xor_b64 s[18:19], s[18:19], s[12:13]
	s_xor_b64 s[20:21], s[20:21], s[12:13]
	v_cndmask_b32_e64 v188, v188, v10, s[14:15]
	v_cndmask_b32_e64 v189, v189, v11, s[14:15]
	v_cndmask_b32_e64 v190, v190, v12, s[16:17]
	v_cndmask_b32_e64 v191, v191, v13, s[16:17]
	v_cndmask_b32_e64 v192, v192, v14, s[18:19]
	v_cndmask_b32_e64 v193, v193, v15, s[18:19]
	v_cndmask_b32_e64 v194, v194, v16, s[20:21]
	v_cndmask_b32_e64 v195, v195, v17, s[20:21]
	s_xnor_b64 s[12:13], s[8:9], s[2:3]
	ds_bpermute_b32 v10, v197, v188
	ds_bpermute_b32 v11, v197, v189
	ds_bpermute_b32 v12, v197, v190
	ds_bpermute_b32 v13, v197, v191
	ds_bpermute_b32 v14, v197, v192
	ds_bpermute_b32 v15, v197, v193
	ds_bpermute_b32 v16, v197, v194
	ds_bpermute_b32 v17, v197, v195
	s_waitcnt lgkmcnt(6)
	v_cmp_gt_u64_e64 s[14:15], v[188:189], v[10:11]
	s_waitcnt lgkmcnt(4)
	v_cmp_gt_u64_e64 s[16:17], v[190:191], v[12:13]
	s_waitcnt lgkmcnt(2)
	v_cmp_gt_u64_e64 s[18:19], v[192:193], v[14:15]
	s_waitcnt lgkmcnt(0)
	v_cmp_gt_u64_e64 s[20:21], v[194:195], v[16:17]
	s_xor_b64 s[14:15], s[14:15], s[12:13]
	s_xor_b64 s[16:17], s[16:17], s[12:13]
	s_xor_b64 s[18:19], s[18:19], s[12:13]
	s_xor_b64 s[20:21], s[20:21], s[12:13]
	v_cndmask_b32_e64 v188, v188, v10, s[14:15]
	v_cndmask_b32_e64 v189, v189, v11, s[14:15]
	v_cndmask_b32_e64 v190, v190, v12, s[16:17]
	v_cndmask_b32_e64 v191, v191, v13, s[16:17]
	v_cndmask_b32_e64 v192, v192, v14, s[18:19]
	v_cndmask_b32_e64 v193, v193, v15, s[18:19]
	v_cndmask_b32_e64 v194, v194, v16, s[20:21]
	v_cndmask_b32_e64 v195, v195, v17, s[20:21]
	s_xnor_b64 s[12:13], s[8:9], s[0:1]
	ds_bpermute_b32 v10, v196, v188
	ds_bpermute_b32 v11, v196, v189
	ds_bpermute_b32 v12, v196, v190
	ds_bpermute_b32 v13, v196, v191
	ds_bpermute_b32 v14, v196, v192
	ds_bpermute_b32 v15, v196, v193
	ds_bpermute_b32 v16, v196, v194
	ds_bpermute_b32 v17, v196, v195
	s_waitcnt lgkmcnt(6)
	v_cmp_gt_u64_e64 s[14:15], v[188:189], v[10:11]
	s_waitcnt lgkmcnt(4)
	v_cmp_gt_u64_e64 s[16:17], v[190:191], v[12:13]
	s_waitcnt lgkmcnt(2)
	v_cmp_gt_u64_e64 s[18:19], v[192:193], v[14:15]
	s_waitcnt lgkmcnt(0)
	v_cmp_gt_u64_e64 s[20:21], v[194:195], v[16:17]
	s_xor_b64 s[14:15], s[14:15], s[12:13]
	s_xor_b64 s[16:17], s[16:17], s[12:13]
	s_xor_b64 s[18:19], s[18:19], s[12:13]
	s_xor_b64 s[20:21], s[20:21], s[12:13]
	v_cndmask_b32_e64 v188, v188, v10, s[14:15]
	v_cndmask_b32_e64 v189, v189, v11, s[14:15]
	v_cndmask_b32_e64 v190, v190, v12, s[16:17]
	v_cndmask_b32_e64 v191, v191, v13, s[16:17]
	v_cndmask_b32_e64 v192, v192, v14, s[18:19]
	v_cndmask_b32_e64 v193, v193, v15, s[18:19]
	v_cndmask_b32_e64 v194, v194, v16, s[20:21]
	v_cndmask_b32_e64 v195, v195, v17, s[20:21]
	s_not_b64 s[12:13], s[8:9]
	v_cmp_gt_u64_e64 s[14:15], v[188:189], v[192:193]
	v_cmp_gt_u64_e64 s[16:17], v[190:191], v[194:195]
	s_xor_b64 s[14:15], s[14:15], s[12:13]
	s_xor_b64 s[16:17], s[16:17], s[12:13]
	v_cndmask_b32_e64 v2, v188, v192, s[14:15]
	v_cndmask_b32_e64 v3, v189, v193, s[14:15]
	v_cndmask_b32_e64 v6, v192, v188, s[14:15]
	v_cndmask_b32_e64 v7, v193, v189, s[14:15]
	v_cndmask_b32_e64 v4, v190, v194, s[16:17]
	v_cndmask_b32_e64 v5, v191, v195, s[16:17]
	v_cndmask_b32_e64 v8, v194, v190, s[16:17]
	v_cndmask_b32_e64 v9, v195, v191, s[16:17]
	s_not_b64 s[12:13], s[8:9]
	v_cmp_gt_u64_e64 s[14:15], v[2:3], v[4:5]
	v_cmp_gt_u64_e64 s[16:17], v[6:7], v[8:9]
	s_xor_b64 s[14:15], s[14:15], s[12:13]
	s_xor_b64 s[16:17], s[16:17], s[12:13]
	v_cndmask_b32_e64 v188, v2, v4, s[14:15]
	v_cndmask_b32_e64 v189, v3, v5, s[14:15]
	v_cndmask_b32_e64 v190, v4, v2, s[14:15]
	v_cndmask_b32_e64 v191, v5, v3, s[14:15]
	v_cndmask_b32_e64 v192, v6, v8, s[16:17]
	v_cndmask_b32_e64 v193, v7, v9, s[16:17]
	v_cndmask_b32_e64 v194, v8, v6, s[16:17]
	v_cndmask_b32_e64 v195, v9, v7, s[16:17]
	s_xnor_b64 s[12:13], s[10:11], s[8:9]
	ds_bpermute_b32 v10, v200, v188
	ds_bpermute_b32 v11, v200, v189
	ds_bpermute_b32 v12, v200, v190
	ds_bpermute_b32 v13, v200, v191
	ds_bpermute_b32 v14, v200, v192
	ds_bpermute_b32 v15, v200, v193
	ds_bpermute_b32 v16, v200, v194
	ds_bpermute_b32 v17, v200, v195
	s_waitcnt lgkmcnt(6)
	v_cmp_gt_u64_e64 s[14:15], v[188:189], v[10:11]
	s_waitcnt lgkmcnt(4)
	v_cmp_gt_u64_e64 s[16:17], v[190:191], v[12:13]
	s_waitcnt lgkmcnt(2)
	v_cmp_gt_u64_e64 s[18:19], v[192:193], v[14:15]
	s_waitcnt lgkmcnt(0)
	v_cmp_gt_u64_e64 s[20:21], v[194:195], v[16:17]
	s_xor_b64 s[14:15], s[14:15], s[12:13]
	s_xor_b64 s[16:17], s[16:17], s[12:13]
	s_xor_b64 s[18:19], s[18:19], s[12:13]
	s_xor_b64 s[20:21], s[20:21], s[12:13]
	v_cndmask_b32_e64 v188, v188, v10, s[14:15]
	v_cndmask_b32_e64 v189, v189, v11, s[14:15]
	v_cndmask_b32_e64 v190, v190, v12, s[16:17]
	v_cndmask_b32_e64 v191, v191, v13, s[16:17]
	v_cndmask_b32_e64 v192, v192, v14, s[18:19]
	v_cndmask_b32_e64 v193, v193, v15, s[18:19]
	v_cndmask_b32_e64 v194, v194, v16, s[20:21]
	v_cndmask_b32_e64 v195, v195, v17, s[20:21]
	s_xnor_b64 s[12:13], s[10:11], s[6:7]
	ds_bpermute_b32 v10, v199, v188
	ds_bpermute_b32 v11, v199, v189
	ds_bpermute_b32 v12, v199, v190
	ds_bpermute_b32 v13, v199, v191
	ds_bpermute_b32 v14, v199, v192
	ds_bpermute_b32 v15, v199, v193
	ds_bpermute_b32 v16, v199, v194
	ds_bpermute_b32 v17, v199, v195
	s_waitcnt lgkmcnt(6)
	v_cmp_gt_u64_e64 s[14:15], v[188:189], v[10:11]
	s_waitcnt lgkmcnt(4)
	v_cmp_gt_u64_e64 s[16:17], v[190:191], v[12:13]
	s_waitcnt lgkmcnt(2)
	v_cmp_gt_u64_e64 s[18:19], v[192:193], v[14:15]
	s_waitcnt lgkmcnt(0)
	v_cmp_gt_u64_e64 s[20:21], v[194:195], v[16:17]
	s_xor_b64 s[14:15], s[14:15], s[12:13]
	s_xor_b64 s[16:17], s[16:17], s[12:13]
	s_xor_b64 s[18:19], s[18:19], s[12:13]
	s_xor_b64 s[20:21], s[20:21], s[12:13]
	v_cndmask_b32_e64 v188, v188, v10, s[14:15]
	v_cndmask_b32_e64 v189, v189, v11, s[14:15]
	v_cndmask_b32_e64 v190, v190, v12, s[16:17]
	v_cndmask_b32_e64 v191, v191, v13, s[16:17]
	v_cndmask_b32_e64 v192, v192, v14, s[18:19]
	v_cndmask_b32_e64 v193, v193, v15, s[18:19]
	v_cndmask_b32_e64 v194, v194, v16, s[20:21]
	v_cndmask_b32_e64 v195, v195, v17, s[20:21]
	s_xnor_b64 s[12:13], s[10:11], s[4:5]
	ds_bpermute_b32 v10, v198, v188
	ds_bpermute_b32 v11, v198, v189
	ds_bpermute_b32 v12, v198, v190
	ds_bpermute_b32 v13, v198, v191
	ds_bpermute_b32 v14, v198, v192
	ds_bpermute_b32 v15, v198, v193
	ds_bpermute_b32 v16, v198, v194
	ds_bpermute_b32 v17, v198, v195
	s_waitcnt lgkmcnt(6)
	v_cmp_gt_u64_e64 s[14:15], v[188:189], v[10:11]
	s_waitcnt lgkmcnt(4)
	v_cmp_gt_u64_e64 s[16:17], v[190:191], v[12:13]
	s_waitcnt lgkmcnt(2)
	v_cmp_gt_u64_e64 s[18:19], v[192:193], v[14:15]
	s_waitcnt lgkmcnt(0)
	v_cmp_gt_u64_e64 s[20:21], v[194:195], v[16:17]
	s_xor_b64 s[14:15], s[14:15], s[12:13]
	s_xor_b64 s[16:17], s[16:17], s[12:13]
	s_xor_b64 s[18:19], s[18:19], s[12:13]
	s_xor_b64 s[20:21], s[20:21], s[12:13]
	v_cndmask_b32_e64 v188, v188, v10, s[14:15]
	v_cndmask_b32_e64 v189, v189, v11, s[14:15]
	v_cndmask_b32_e64 v190, v190, v12, s[16:17]
	v_cndmask_b32_e64 v191, v191, v13, s[16:17]
	v_cndmask_b32_e64 v192, v192, v14, s[18:19]
	v_cndmask_b32_e64 v193, v193, v15, s[18:19]
	v_cndmask_b32_e64 v194, v194, v16, s[20:21]
	v_cndmask_b32_e64 v195, v195, v17, s[20:21]
	s_xnor_b64 s[12:13], s[10:11], s[2:3]
	ds_bpermute_b32 v10, v197, v188
	ds_bpermute_b32 v11, v197, v189
	ds_bpermute_b32 v12, v197, v190
	ds_bpermute_b32 v13, v197, v191
	ds_bpermute_b32 v14, v197, v192
	ds_bpermute_b32 v15, v197, v193
	ds_bpermute_b32 v16, v197, v194
	ds_bpermute_b32 v17, v197, v195
	s_waitcnt lgkmcnt(6)
	v_cmp_gt_u64_e64 s[14:15], v[188:189], v[10:11]
	s_waitcnt lgkmcnt(4)
	v_cmp_gt_u64_e64 s[16:17], v[190:191], v[12:13]
	s_waitcnt lgkmcnt(2)
	v_cmp_gt_u64_e64 s[18:19], v[192:193], v[14:15]
	s_waitcnt lgkmcnt(0)
	v_cmp_gt_u64_e64 s[20:21], v[194:195], v[16:17]
	s_xor_b64 s[14:15], s[14:15], s[12:13]
	s_xor_b64 s[16:17], s[16:17], s[12:13]
	s_xor_b64 s[18:19], s[18:19], s[12:13]
	s_xor_b64 s[20:21], s[20:21], s[12:13]
	v_cndmask_b32_e64 v188, v188, v10, s[14:15]
	v_cndmask_b32_e64 v189, v189, v11, s[14:15]
	v_cndmask_b32_e64 v190, v190, v12, s[16:17]
	v_cndmask_b32_e64 v191, v191, v13, s[16:17]
	v_cndmask_b32_e64 v192, v192, v14, s[18:19]
	v_cndmask_b32_e64 v193, v193, v15, s[18:19]
	v_cndmask_b32_e64 v194, v194, v16, s[20:21]
	v_cndmask_b32_e64 v195, v195, v17, s[20:21]
	s_xnor_b64 s[12:13], s[10:11], s[0:1]
	ds_bpermute_b32 v10, v196, v188
	ds_bpermute_b32 v11, v196, v189
	ds_bpermute_b32 v12, v196, v190
	ds_bpermute_b32 v13, v196, v191
	ds_bpermute_b32 v14, v196, v192
	ds_bpermute_b32 v15, v196, v193
	ds_bpermute_b32 v16, v196, v194
	ds_bpermute_b32 v17, v196, v195
	s_waitcnt lgkmcnt(6)
	v_cmp_gt_u64_e64 s[14:15], v[188:189], v[10:11]
	s_waitcnt lgkmcnt(4)
	v_cmp_gt_u64_e64 s[16:17], v[190:191], v[12:13]
	s_waitcnt lgkmcnt(2)
	v_cmp_gt_u64_e64 s[18:19], v[192:193], v[14:15]
	s_waitcnt lgkmcnt(0)
	v_cmp_gt_u64_e64 s[20:21], v[194:195], v[16:17]
	s_xor_b64 s[14:15], s[14:15], s[12:13]
	s_xor_b64 s[16:17], s[16:17], s[12:13]
	s_xor_b64 s[18:19], s[18:19], s[12:13]
	s_xor_b64 s[20:21], s[20:21], s[12:13]
	v_cndmask_b32_e64 v188, v188, v10, s[14:15]
	v_cndmask_b32_e64 v189, v189, v11, s[14:15]
	v_cndmask_b32_e64 v190, v190, v12, s[16:17]
	v_cndmask_b32_e64 v191, v191, v13, s[16:17]
	v_cndmask_b32_e64 v192, v192, v14, s[18:19]
	v_cndmask_b32_e64 v193, v193, v15, s[18:19]
	v_cndmask_b32_e64 v194, v194, v16, s[20:21]
	v_cndmask_b32_e64 v195, v195, v17, s[20:21]
	s_not_b64 s[12:13], s[10:11]
	v_cmp_gt_u64_e64 s[14:15], v[188:189], v[192:193]
	v_cmp_gt_u64_e64 s[16:17], v[190:191], v[194:195]
	s_xor_b64 s[14:15], s[14:15], s[12:13]
	s_xor_b64 s[16:17], s[16:17], s[12:13]
	v_cndmask_b32_e64 v2, v188, v192, s[14:15]
	v_cndmask_b32_e64 v3, v189, v193, s[14:15]
	v_cndmask_b32_e64 v6, v192, v188, s[14:15]
	v_cndmask_b32_e64 v7, v193, v189, s[14:15]
	v_cndmask_b32_e64 v4, v190, v194, s[16:17]
	v_cndmask_b32_e64 v5, v191, v195, s[16:17]
	v_cndmask_b32_e64 v8, v194, v190, s[16:17]
	v_cndmask_b32_e64 v9, v195, v191, s[16:17]
	s_not_b64 s[12:13], s[10:11]
	v_cmp_gt_u64_e64 s[14:15], v[2:3], v[4:5]
	v_cmp_gt_u64_e64 s[16:17], v[6:7], v[8:9]
	s_xor_b64 s[14:15], s[14:15], s[12:13]
	s_xor_b64 s[16:17], s[16:17], s[12:13]
	v_cndmask_b32_e64 v188, v2, v4, s[14:15]
	v_cndmask_b32_e64 v189, v3, v5, s[14:15]
	v_cndmask_b32_e64 v190, v4, v2, s[14:15]
	v_cndmask_b32_e64 v191, v5, v3, s[14:15]
	v_cndmask_b32_e64 v192, v6, v8, s[16:17]
	v_cndmask_b32_e64 v193, v7, v9, s[16:17]
	v_cndmask_b32_e64 v194, v8, v6, s[16:17]
	v_cndmask_b32_e64 v195, v9, v7, s[16:17]
	s_not_b64 s[12:13], s[10:11]
	s_bitcmp1_b32 s22, 0
	s_cselect_b64 s[12:13], s[10:11], s[12:13]
	ds_bpermute_b32 v10, v201, v188
	ds_bpermute_b32 v11, v201, v189
	ds_bpermute_b32 v12, v201, v190
	ds_bpermute_b32 v13, v201, v191
	ds_bpermute_b32 v14, v201, v192
	ds_bpermute_b32 v15, v201, v193
	ds_bpermute_b32 v16, v201, v194
	ds_bpermute_b32 v17, v201, v195
	s_waitcnt lgkmcnt(6)
	v_cmp_gt_u64_e64 s[14:15], v[188:189], v[10:11]
	s_waitcnt lgkmcnt(4)
	v_cmp_gt_u64_e64 s[16:17], v[190:191], v[12:13]
	s_waitcnt lgkmcnt(2)
	v_cmp_gt_u64_e64 s[18:19], v[192:193], v[14:15]
	s_waitcnt lgkmcnt(0)
	v_cmp_gt_u64_e64 s[20:21], v[194:195], v[16:17]
	s_xor_b64 s[14:15], s[14:15], s[12:13]
	s_xor_b64 s[16:17], s[16:17], s[12:13]
	s_xor_b64 s[18:19], s[18:19], s[12:13]
	s_xor_b64 s[20:21], s[20:21], s[12:13]
	v_cndmask_b32_e64 v188, v188, v10, s[14:15]
	v_cndmask_b32_e64 v189, v189, v11, s[14:15]
	v_cndmask_b32_e64 v190, v190, v12, s[16:17]
	v_cndmask_b32_e64 v191, v191, v13, s[16:17]
	v_cndmask_b32_e64 v192, v192, v14, s[18:19]
	v_cndmask_b32_e64 v193, v193, v15, s[18:19]
	v_cndmask_b32_e64 v194, v194, v16, s[20:21]
	v_cndmask_b32_e64 v195, v195, v17, s[20:21]
	s_not_b64 s[12:13], s[8:9]
	s_bitcmp1_b32 s22, 0
	s_cselect_b64 s[12:13], s[8:9], s[12:13]
	ds_bpermute_b32 v10, v200, v188
	ds_bpermute_b32 v11, v200, v189
	ds_bpermute_b32 v12, v200, v190
	ds_bpermute_b32 v13, v200, v191
	ds_bpermute_b32 v14, v200, v192
	ds_bpermute_b32 v15, v200, v193
	ds_bpermute_b32 v16, v200, v194
	ds_bpermute_b32 v17, v200, v195
	s_waitcnt lgkmcnt(6)
	v_cmp_gt_u64_e64 s[14:15], v[188:189], v[10:11]
	s_waitcnt lgkmcnt(4)
	v_cmp_gt_u64_e64 s[16:17], v[190:191], v[12:13]
	s_waitcnt lgkmcnt(2)
	v_cmp_gt_u64_e64 s[18:19], v[192:193], v[14:15]
	s_waitcnt lgkmcnt(0)
	v_cmp_gt_u64_e64 s[20:21], v[194:195], v[16:17]
	s_xor_b64 s[14:15], s[14:15], s[12:13]
	s_xor_b64 s[16:17], s[16:17], s[12:13]
	s_xor_b64 s[18:19], s[18:19], s[12:13]
	s_xor_b64 s[20:21], s[20:21], s[12:13]
	v_cndmask_b32_e64 v188, v188, v10, s[14:15]
	v_cndmask_b32_e64 v189, v189, v11, s[14:15]
	v_cndmask_b32_e64 v190, v190, v12, s[16:17]
	v_cndmask_b32_e64 v191, v191, v13, s[16:17]
	v_cndmask_b32_e64 v192, v192, v14, s[18:19]
	v_cndmask_b32_e64 v193, v193, v15, s[18:19]
	v_cndmask_b32_e64 v194, v194, v16, s[20:21]
	v_cndmask_b32_e64 v195, v195, v17, s[20:21]
	s_not_b64 s[12:13], s[6:7]
	s_bitcmp1_b32 s22, 0
	s_cselect_b64 s[12:13], s[6:7], s[12:13]
	ds_bpermute_b32 v10, v199, v188
	ds_bpermute_b32 v11, v199, v189
	ds_bpermute_b32 v12, v199, v190
	ds_bpermute_b32 v13, v199, v191
	ds_bpermute_b32 v14, v199, v192
	ds_bpermute_b32 v15, v199, v193
	ds_bpermute_b32 v16, v199, v194
	ds_bpermute_b32 v17, v199, v195
	s_waitcnt lgkmcnt(6)
	v_cmp_gt_u64_e64 s[14:15], v[188:189], v[10:11]
	s_waitcnt lgkmcnt(4)
	v_cmp_gt_u64_e64 s[16:17], v[190:191], v[12:13]
	s_waitcnt lgkmcnt(2)
	v_cmp_gt_u64_e64 s[18:19], v[192:193], v[14:15]
	s_waitcnt lgkmcnt(0)
	v_cmp_gt_u64_e64 s[20:21], v[194:195], v[16:17]
	s_xor_b64 s[14:15], s[14:15], s[12:13]
	s_xor_b64 s[16:17], s[16:17], s[12:13]
	s_xor_b64 s[18:19], s[18:19], s[12:13]
	s_xor_b64 s[20:21], s[20:21], s[12:13]
	v_cndmask_b32_e64 v188, v188, v10, s[14:15]
	v_cndmask_b32_e64 v189, v189, v11, s[14:15]
	v_cndmask_b32_e64 v190, v190, v12, s[16:17]
	v_cndmask_b32_e64 v191, v191, v13, s[16:17]
	v_cndmask_b32_e64 v192, v192, v14, s[18:19]
	v_cndmask_b32_e64 v193, v193, v15, s[18:19]
	v_cndmask_b32_e64 v194, v194, v16, s[20:21]
	v_cndmask_b32_e64 v195, v195, v17, s[20:21]
	s_not_b64 s[12:13], s[4:5]
	s_bitcmp1_b32 s22, 0
	s_cselect_b64 s[12:13], s[4:5], s[12:13]
	ds_bpermute_b32 v10, v198, v188
	ds_bpermute_b32 v11, v198, v189
	ds_bpermute_b32 v12, v198, v190
	ds_bpermute_b32 v13, v198, v191
	ds_bpermute_b32 v14, v198, v192
	ds_bpermute_b32 v15, v198, v193
	ds_bpermute_b32 v16, v198, v194
	ds_bpermute_b32 v17, v198, v195
	s_waitcnt lgkmcnt(6)
	v_cmp_gt_u64_e64 s[14:15], v[188:189], v[10:11]
	s_waitcnt lgkmcnt(4)
	v_cmp_gt_u64_e64 s[16:17], v[190:191], v[12:13]
	s_waitcnt lgkmcnt(2)
	v_cmp_gt_u64_e64 s[18:19], v[192:193], v[14:15]
	s_waitcnt lgkmcnt(0)
	v_cmp_gt_u64_e64 s[20:21], v[194:195], v[16:17]
	s_xor_b64 s[14:15], s[14:15], s[12:13]
	s_xor_b64 s[16:17], s[16:17], s[12:13]
	s_xor_b64 s[18:19], s[18:19], s[12:13]
	s_xor_b64 s[20:21], s[20:21], s[12:13]
	v_cndmask_b32_e64 v188, v188, v10, s[14:15]
	v_cndmask_b32_e64 v189, v189, v11, s[14:15]
	v_cndmask_b32_e64 v190, v190, v12, s[16:17]
	v_cndmask_b32_e64 v191, v191, v13, s[16:17]
	v_cndmask_b32_e64 v192, v192, v14, s[18:19]
	v_cndmask_b32_e64 v193, v193, v15, s[18:19]
	v_cndmask_b32_e64 v194, v194, v16, s[20:21]
	v_cndmask_b32_e64 v195, v195, v17, s[20:21]
	s_not_b64 s[12:13], s[2:3]
	s_bitcmp1_b32 s22, 0
	s_cselect_b64 s[12:13], s[2:3], s[12:13]
	ds_bpermute_b32 v10, v197, v188
	ds_bpermute_b32 v11, v197, v189
	ds_bpermute_b32 v12, v197, v190
	ds_bpermute_b32 v13, v197, v191
	ds_bpermute_b32 v14, v197, v192
	ds_bpermute_b32 v15, v197, v193
	ds_bpermute_b32 v16, v197, v194
	ds_bpermute_b32 v17, v197, v195
	s_waitcnt lgkmcnt(6)
	v_cmp_gt_u64_e64 s[14:15], v[188:189], v[10:11]
	s_waitcnt lgkmcnt(4)
	v_cmp_gt_u64_e64 s[16:17], v[190:191], v[12:13]
	s_waitcnt lgkmcnt(2)
	v_cmp_gt_u64_e64 s[18:19], v[192:193], v[14:15]
	s_waitcnt lgkmcnt(0)
	v_cmp_gt_u64_e64 s[20:21], v[194:195], v[16:17]
	s_xor_b64 s[14:15], s[14:15], s[12:13]
	s_xor_b64 s[16:17], s[16:17], s[12:13]
	s_xor_b64 s[18:19], s[18:19], s[12:13]
	s_xor_b64 s[20:21], s[20:21], s[12:13]
	v_cndmask_b32_e64 v188, v188, v10, s[14:15]
	v_cndmask_b32_e64 v189, v189, v11, s[14:15]
	v_cndmask_b32_e64 v190, v190, v12, s[16:17]
	v_cndmask_b32_e64 v191, v191, v13, s[16:17]
	v_cndmask_b32_e64 v192, v192, v14, s[18:19]
	v_cndmask_b32_e64 v193, v193, v15, s[18:19]
	v_cndmask_b32_e64 v194, v194, v16, s[20:21]
	v_cndmask_b32_e64 v195, v195, v17, s[20:21]
	s_not_b64 s[12:13], s[0:1]
	s_bitcmp1_b32 s22, 0
	s_cselect_b64 s[12:13], s[0:1], s[12:13]
	ds_bpermute_b32 v10, v196, v188
	ds_bpermute_b32 v11, v196, v189
	ds_bpermute_b32 v12, v196, v190
	ds_bpermute_b32 v13, v196, v191
	ds_bpermute_b32 v14, v196, v192
	ds_bpermute_b32 v15, v196, v193
	ds_bpermute_b32 v16, v196, v194
	ds_bpermute_b32 v17, v196, v195
	s_waitcnt lgkmcnt(6)
	v_cmp_gt_u64_e64 s[14:15], v[188:189], v[10:11]
	s_waitcnt lgkmcnt(4)
	v_cmp_gt_u64_e64 s[16:17], v[190:191], v[12:13]
	s_waitcnt lgkmcnt(2)
	v_cmp_gt_u64_e64 s[18:19], v[192:193], v[14:15]
	s_waitcnt lgkmcnt(0)
	v_cmp_gt_u64_e64 s[20:21], v[194:195], v[16:17]
	s_xor_b64 s[14:15], s[14:15], s[12:13]
	s_xor_b64 s[16:17], s[16:17], s[12:13]
	s_xor_b64 s[18:19], s[18:19], s[12:13]
	s_xor_b64 s[20:21], s[20:21], s[12:13]
	v_cndmask_b32_e64 v188, v188, v10, s[14:15]
	v_cndmask_b32_e64 v189, v189, v11, s[14:15]
	v_cndmask_b32_e64 v190, v190, v12, s[16:17]
	v_cndmask_b32_e64 v191, v191, v13, s[16:17]
	v_cndmask_b32_e64 v192, v192, v14, s[18:19]
	v_cndmask_b32_e64 v193, v193, v15, s[18:19]
	v_cndmask_b32_e64 v194, v194, v16, s[20:21]
	v_cndmask_b32_e64 v195, v195, v17, s[20:21]
	s_bitcmp0_b32 s22, 0
	s_cselect_b64 s[12:13], -1, 0
	v_cmp_gt_u64_e64 s[14:15], v[188:189], v[192:193]
	v_cmp_gt_u64_e64 s[16:17], v[190:191], v[194:195]
	s_xor_b64 s[14:15], s[14:15], s[12:13]
	s_xor_b64 s[16:17], s[16:17], s[12:13]
	v_cndmask_b32_e64 v2, v188, v192, s[14:15]
	v_cndmask_b32_e64 v3, v189, v193, s[14:15]
	v_cndmask_b32_e64 v6, v192, v188, s[14:15]
	v_cndmask_b32_e64 v7, v193, v189, s[14:15]
	v_cndmask_b32_e64 v4, v190, v194, s[16:17]
	v_cndmask_b32_e64 v5, v191, v195, s[16:17]
	v_cndmask_b32_e64 v8, v194, v190, s[16:17]
	v_cndmask_b32_e64 v9, v195, v191, s[16:17]
	s_bitcmp0_b32 s22, 0
	s_cselect_b64 s[12:13], -1, 0
	v_cmp_gt_u64_e64 s[14:15], v[2:3], v[4:5]
	v_cmp_gt_u64_e64 s[16:17], v[6:7], v[8:9]
	s_xor_b64 s[14:15], s[14:15], s[12:13]
	s_xor_b64 s[16:17], s[16:17], s[12:13]
	v_cndmask_b32_e64 v188, v2, v4, s[14:15]
	v_cndmask_b32_e64 v189, v3, v5, s[14:15]
	v_cndmask_b32_e64 v190, v4, v2, s[14:15]
	v_cndmask_b32_e64 v191, v5, v3, s[14:15]
	v_cndmask_b32_e64 v192, v6, v8, s[16:17]
	v_cndmask_b32_e64 v193, v7, v9, s[16:17]
	v_cndmask_b32_e64 v194, v8, v6, s[16:17]
	v_cndmask_b32_e64 v195, v9, v7, s[16:17]
	s_cmp_ge_i32 s24, 0x100
	s_cbranch_scc1 .Ltks_short
	s_lshr_b32 s98, s22, 1
	s_lshr_b32 s99, s22, 0
	s_xor_b32 s98, s98, s99
	s_bitcmp0_b32 s98, 0
	s_cselect_b64 s[12:13], -1, 0
	ds_write_b128 v202, v[188:191]
	ds_write_b128 v202, v[192:195] offset:16
	s_waitcnt lgkmcnt(0)
	s_barrier
	ds_read_b128 v[10:13], v203
	ds_read_b128 v[14:17], v203 offset:16
	s_waitcnt lgkmcnt(1)
	v_cmp_gt_u64_e64 s[14:15], v[188:189], v[10:11]
	v_cmp_gt_u64_e64 s[16:17], v[190:191], v[12:13]
	s_waitcnt lgkmcnt(0)
	v_cmp_gt_u64_e64 s[18:19], v[192:193], v[14:15]
	v_cmp_gt_u64_e64 s[20:21], v[194:195], v[16:17]
	s_xor_b64 s[14:15], s[14:15], s[12:13]
	s_xor_b64 s[16:17], s[16:17], s[12:13]
	s_xor_b64 s[18:19], s[18:19], s[12:13]
	s_xor_b64 s[20:21], s[20:21], s[12:13]
	v_cndmask_b32_e64 v188, v188, v10, s[14:15]
	v_cndmask_b32_e64 v189, v189, v11, s[14:15]
	v_cndmask_b32_e64 v190, v190, v12, s[16:17]
	v_cndmask_b32_e64 v191, v191, v13, s[16:17]
	v_cndmask_b32_e64 v192, v192, v14, s[18:19]
	v_cndmask_b32_e64 v193, v193, v15, s[18:19]
	v_cndmask_b32_e64 v194, v194, v16, s[20:21]
	v_cndmask_b32_e64 v195, v195, v17, s[20:21]
	s_not_b64 s[12:13], s[10:11]
	s_bitcmp1_b32 s22, 1
	s_cselect_b64 s[12:13], s[10:11], s[12:13]
	ds_bpermute_b32 v10, v201, v188
	ds_bpermute_b32 v11, v201, v189
	ds_bpermute_b32 v12, v201, v190
	ds_bpermute_b32 v13, v201, v191
	ds_bpermute_b32 v14, v201, v192
	ds_bpermute_b32 v15, v201, v193
	ds_bpermute_b32 v16, v201, v194
	ds_bpermute_b32 v17, v201, v195
	s_waitcnt lgkmcnt(6)
	v_cmp_gt_u64_e64 s[14:15], v[188:189], v[10:11]
	s_waitcnt lgkmcnt(4)
	v_cmp_gt_u64_e64 s[16:17], v[190:191], v[12:13]
	s_waitcnt lgkmcnt(2)
	v_cmp_gt_u64_e64 s[18:19], v[192:193], v[14:15]
	s_waitcnt lgkmcnt(0)
	v_cmp_gt_u64_e64 s[20:21], v[194:195], v[16:17]
	s_xor_b64 s[14:15], s[14:15], s[12:13]
	s_xor_b64 s[16:17], s[16:17], s[12:13]
	s_xor_b64 s[18:19], s[18:19], s[12:13]
	s_xor_b64 s[20:21], s[20:21], s[12:13]
	v_cndmask_b32_e64 v188, v188, v10, s[14:15]
	v_cndmask_b32_e64 v189, v189, v11, s[14:15]
	v_cndmask_b32_e64 v190, v190, v12, s[16:17]
	v_cndmask_b32_e64 v191, v191, v13, s[16:17]
	v_cndmask_b32_e64 v192, v192, v14, s[18:19]
	v_cndmask_b32_e64 v193, v193, v15, s[18:19]
	v_cndmask_b32_e64 v194, v194, v16, s[20:21]
	v_cndmask_b32_e64 v195, v195, v17, s[20:21]
	s_not_b64 s[12:13], s[8:9]
	s_bitcmp1_b32 s22, 1
	s_cselect_b64 s[12:13], s[8:9], s[12:13]
	ds_bpermute_b32 v10, v200, v188
	ds_bpermute_b32 v11, v200, v189
	ds_bpermute_b32 v12, v200, v190
	ds_bpermute_b32 v13, v200, v191
	ds_bpermute_b32 v14, v200, v192
	ds_bpermute_b32 v15, v200, v193
	ds_bpermute_b32 v16, v200, v194
	ds_bpermute_b32 v17, v200, v195
	s_waitcnt lgkmcnt(6)
	v_cmp_gt_u64_e64 s[14:15], v[188:189], v[10:11]
	s_waitcnt lgkmcnt(4)
	v_cmp_gt_u64_e64 s[16:17], v[190:191], v[12:13]
	s_waitcnt lgkmcnt(2)
	v_cmp_gt_u64_e64 s[18:19], v[192:193], v[14:15]
	s_waitcnt lgkmcnt(0)
	v_cmp_gt_u64_e64 s[20:21], v[194:195], v[16:17]
	s_xor_b64 s[14:15], s[14:15], s[12:13]
	s_xor_b64 s[16:17], s[16:17], s[12:13]
	s_xor_b64 s[18:19], s[18:19], s[12:13]
	s_xor_b64 s[20:21], s[20:21], s[12:13]
	v_cndmask_b32_e64 v188, v188, v10, s[14:15]
	v_cndmask_b32_e64 v189, v189, v11, s[14:15]
	v_cndmask_b32_e64 v190, v190, v12, s[16:17]
	v_cndmask_b32_e64 v191, v191, v13, s[16:17]
	v_cndmask_b32_e64 v192, v192, v14, s[18:19]
	v_cndmask_b32_e64 v193, v193, v15, s[18:19]
	v_cndmask_b32_e64 v194, v194, v16, s[20:21]
	v_cndmask_b32_e64 v195, v195, v17, s[20:21]
	s_not_b64 s[12:13], s[6:7]
	s_bitcmp1_b32 s22, 1
	s_cselect_b64 s[12:13], s[6:7], s[12:13]
	ds_bpermute_b32 v10, v199, v188
	ds_bpermute_b32 v11, v199, v189
	ds_bpermute_b32 v12, v199, v190
	ds_bpermute_b32 v13, v199, v191
	ds_bpermute_b32 v14, v199, v192
	ds_bpermute_b32 v15, v199, v193
	ds_bpermute_b32 v16, v199, v194
	ds_bpermute_b32 v17, v199, v195
	s_waitcnt lgkmcnt(6)
	v_cmp_gt_u64_e64 s[14:15], v[188:189], v[10:11]
	s_waitcnt lgkmcnt(4)
	v_cmp_gt_u64_e64 s[16:17], v[190:191], v[12:13]
	s_waitcnt lgkmcnt(2)
	v_cmp_gt_u64_e64 s[18:19], v[192:193], v[14:15]
	s_waitcnt lgkmcnt(0)
	v_cmp_gt_u64_e64 s[20:21], v[194:195], v[16:17]
	s_xor_b64 s[14:15], s[14:15], s[12:13]
	s_xor_b64 s[16:17], s[16:17], s[12:13]
	s_xor_b64 s[18:19], s[18:19], s[12:13]
	s_xor_b64 s[20:21], s[20:21], s[12:13]
	v_cndmask_b32_e64 v188, v188, v10, s[14:15]
	v_cndmask_b32_e64 v189, v189, v11, s[14:15]
	v_cndmask_b32_e64 v190, v190, v12, s[16:17]
	v_cndmask_b32_e64 v191, v191, v13, s[16:17]
	v_cndmask_b32_e64 v192, v192, v14, s[18:19]
	v_cndmask_b32_e64 v193, v193, v15, s[18:19]
	v_cndmask_b32_e64 v194, v194, v16, s[20:21]
	v_cndmask_b32_e64 v195, v195, v17, s[20:21]
	s_not_b64 s[12:13], s[4:5]
	s_bitcmp1_b32 s22, 1
	s_cselect_b64 s[12:13], s[4:5], s[12:13]
	ds_bpermute_b32 v10, v198, v188
	ds_bpermute_b32 v11, v198, v189
	ds_bpermute_b32 v12, v198, v190
	ds_bpermute_b32 v13, v198, v191
	ds_bpermute_b32 v14, v198, v192
	ds_bpermute_b32 v15, v198, v193
	ds_bpermute_b32 v16, v198, v194
	ds_bpermute_b32 v17, v198, v195
	s_waitcnt lgkmcnt(6)
	v_cmp_gt_u64_e64 s[14:15], v[188:189], v[10:11]
	s_waitcnt lgkmcnt(4)
	v_cmp_gt_u64_e64 s[16:17], v[190:191], v[12:13]
	s_waitcnt lgkmcnt(2)
	v_cmp_gt_u64_e64 s[18:19], v[192:193], v[14:15]
	s_waitcnt lgkmcnt(0)
	v_cmp_gt_u64_e64 s[20:21], v[194:195], v[16:17]
	s_xor_b64 s[14:15], s[14:15], s[12:13]
	s_xor_b64 s[16:17], s[16:17], s[12:13]
	s_xor_b64 s[18:19], s[18:19], s[12:13]
	s_xor_b64 s[20:21], s[20:21], s[12:13]
	v_cndmask_b32_e64 v188, v188, v10, s[14:15]
	v_cndmask_b32_e64 v189, v189, v11, s[14:15]
	v_cndmask_b32_e64 v190, v190, v12, s[16:17]
	v_cndmask_b32_e64 v191, v191, v13, s[16:17]
	v_cndmask_b32_e64 v192, v192, v14, s[18:19]
	v_cndmask_b32_e64 v193, v193, v15, s[18:19]
	v_cndmask_b32_e64 v194, v194, v16, s[20:21]
	v_cndmask_b32_e64 v195, v195, v17, s[20:21]
	s_not_b64 s[12:13], s[2:3]
	s_bitcmp1_b32 s22, 1
	s_cselect_b64 s[12:13], s[2:3], s[12:13]
	ds_bpermute_b32 v10, v197, v188
	ds_bpermute_b32 v11, v197, v189
	ds_bpermute_b32 v12, v197, v190
	ds_bpermute_b32 v13, v197, v191
	ds_bpermute_b32 v14, v197, v192
	ds_bpermute_b32 v15, v197, v193
	ds_bpermute_b32 v16, v197, v194
	ds_bpermute_b32 v17, v197, v195
	s_waitcnt lgkmcnt(6)
	v_cmp_gt_u64_e64 s[14:15], v[188:189], v[10:11]
	s_waitcnt lgkmcnt(4)
	v_cmp_gt_u64_e64 s[16:17], v[190:191], v[12:13]
	s_waitcnt lgkmcnt(2)
	v_cmp_gt_u64_e64 s[18:19], v[192:193], v[14:15]
	s_waitcnt lgkmcnt(0)
	v_cmp_gt_u64_e64 s[20:21], v[194:195], v[16:17]
	s_xor_b64 s[14:15], s[14:15], s[12:13]
	s_xor_b64 s[16:17], s[16:17], s[12:13]
	s_xor_b64 s[18:19], s[18:19], s[12:13]
	s_xor_b64 s[20:21], s[20:21], s[12:13]
	v_cndmask_b32_e64 v188, v188, v10, s[14:15]
	v_cndmask_b32_e64 v189, v189, v11, s[14:15]
	v_cndmask_b32_e64 v190, v190, v12, s[16:17]
	v_cndmask_b32_e64 v191, v191, v13, s[16:17]
	v_cndmask_b32_e64 v192, v192, v14, s[18:19]
	v_cndmask_b32_e64 v193, v193, v15, s[18:19]
	v_cndmask_b32_e64 v194, v194, v16, s[20:21]
	v_cndmask_b32_e64 v195, v195, v17, s[20:21]
	s_not_b64 s[12:13], s[0:1]
	s_bitcmp1_b32 s22, 1
	s_cselect_b64 s[12:13], s[0:1], s[12:13]
	ds_bpermute_b32 v10, v196, v188
	ds_bpermute_b32 v11, v196, v189
	ds_bpermute_b32 v12, v196, v190
	ds_bpermute_b32 v13, v196, v191
	ds_bpermute_b32 v14, v196, v192
	ds_bpermute_b32 v15, v196, v193
	ds_bpermute_b32 v16, v196, v194
	ds_bpermute_b32 v17, v196, v195
	s_waitcnt lgkmcnt(6)
	v_cmp_gt_u64_e64 s[14:15], v[188:189], v[10:11]
	s_waitcnt lgkmcnt(4)
	v_cmp_gt_u64_e64 s[16:17], v[190:191], v[12:13]
	s_waitcnt lgkmcnt(2)
	v_cmp_gt_u64_e64 s[18:19], v[192:193], v[14:15]
	s_waitcnt lgkmcnt(0)
	v_cmp_gt_u64_e64 s[20:21], v[194:195], v[16:17]
	s_xor_b64 s[14:15], s[14:15], s[12:13]
	s_xor_b64 s[16:17], s[16:17], s[12:13]
	s_xor_b64 s[18:19], s[18:19], s[12:13]
	s_xor_b64 s[20:21], s[20:21], s[12:13]
	v_cndmask_b32_e64 v188, v188, v10, s[14:15]
	v_cndmask_b32_e64 v189, v189, v11, s[14:15]
	v_cndmask_b32_e64 v190, v190, v12, s[16:17]
	v_cndmask_b32_e64 v191, v191, v13, s[16:17]
	v_cndmask_b32_e64 v192, v192, v14, s[18:19]
	v_cndmask_b32_e64 v193, v193, v15, s[18:19]
	v_cndmask_b32_e64 v194, v194, v16, s[20:21]
	v_cndmask_b32_e64 v195, v195, v17, s[20:21]
	s_bitcmp0_b32 s22, 1
	s_cselect_b64 s[12:13], -1, 0
	v_cmp_gt_u64_e64 s[14:15], v[188:189], v[192:193]
	v_cmp_gt_u64_e64 s[16:17], v[190:191], v[194:195]
	s_xor_b64 s[14:15], s[14:15], s[12:13]
	s_xor_b64 s[16:17], s[16:17], s[12:13]
	v_cndmask_b32_e64 v2, v188, v192, s[14:15]
	v_cndmask_b32_e64 v3, v189, v193, s[14:15]
	v_cndmask_b32_e64 v6, v192, v188, s[14:15]
	v_cndmask_b32_e64 v7, v193, v189, s[14:15]
	v_cndmask_b32_e64 v4, v190, v194, s[16:17]
	v_cndmask_b32_e64 v5, v191, v195, s[16:17]
	v_cndmask_b32_e64 v8, v194, v190, s[16:17]
	v_cndmask_b32_e64 v9, v195, v191, s[16:17]
	s_bitcmp0_b32 s22, 1
	s_cselect_b64 s[12:13], -1, 0
	v_cmp_gt_u64_e64 s[14:15], v[2:3], v[4:5]
	v_cmp_gt_u64_e64 s[16:17], v[6:7], v[8:9]
	s_xor_b64 s[14:15], s[14:15], s[12:13]
	s_xor_b64 s[16:17], s[16:17], s[12:13]
	v_cndmask_b32_e64 v188, v2, v4, s[14:15]
	v_cndmask_b32_e64 v189, v3, v5, s[14:15]
	v_cndmask_b32_e64 v190, v4, v2, s[14:15]
	v_cndmask_b32_e64 v191, v5, v3, s[14:15]
	v_cndmask_b32_e64 v192, v6, v8, s[16:17]
	v_cndmask_b32_e64 v193, v7, v9, s[16:17]
	v_cndmask_b32_e64 v194, v8, v6, s[16:17]
	v_cndmask_b32_e64 v195, v9, v7, s[16:17]
	s_lshr_b32 s98, s22, 2
	s_lshr_b32 s99, s22, 1
	s_xor_b32 s98, s98, s99
	s_bitcmp0_b32 s98, 0
	s_cselect_b64 s[12:13], -1, 0
	ds_write_b128 v202, v[188:191] offset:16384
	ds_write_b128 v202, v[192:195] offset:16400
	s_waitcnt lgkmcnt(0)
	s_barrier
	ds_read_b128 v[10:13], v204 offset:16384
	ds_read_b128 v[14:17], v204 offset:16400
	s_waitcnt lgkmcnt(1)
	v_cmp_gt_u64_e64 s[14:15], v[188:189], v[10:11]
	v_cmp_gt_u64_e64 s[16:17], v[190:191], v[12:13]
	s_waitcnt lgkmcnt(0)
	v_cmp_gt_u64_e64 s[18:19], v[192:193], v[14:15]
	v_cmp_gt_u64_e64 s[20:21], v[194:195], v[16:17]
	s_xor_b64 s[14:15], s[14:15], s[12:13]
	s_xor_b64 s[16:17], s[16:17], s[12:13]
	s_xor_b64 s[18:19], s[18:19], s[12:13]
	s_xor_b64 s[20:21], s[20:21], s[12:13]
	v_cndmask_b32_e64 v188, v188, v10, s[14:15]
	v_cndmask_b32_e64 v189, v189, v11, s[14:15]
	v_cndmask_b32_e64 v190, v190, v12, s[16:17]
	v_cndmask_b32_e64 v191, v191, v13, s[16:17]
	v_cndmask_b32_e64 v192, v192, v14, s[18:19]
	v_cndmask_b32_e64 v193, v193, v15, s[18:19]
	v_cndmask_b32_e64 v194, v194, v16, s[20:21]
	v_cndmask_b32_e64 v195, v195, v17, s[20:21]
	s_lshr_b32 s98, s22, 2
	s_lshr_b32 s99, s22, 0
	s_xor_b32 s98, s98, s99
	s_bitcmp0_b32 s98, 0
	s_cselect_b64 s[12:13], -1, 0
	ds_write_b128 v202, v[188:191]
	ds_write_b128 v202, v[192:195] offset:16
	s_waitcnt lgkmcnt(0)
	s_barrier
	ds_read_b128 v[10:13], v203
	ds_read_b128 v[14:17], v203 offset:16
	s_waitcnt lgkmcnt(1)
	v_cmp_gt_u64_e64 s[14:15], v[188:189], v[10:11]
	v_cmp_gt_u64_e64 s[16:17], v[190:191], v[12:13]
	s_waitcnt lgkmcnt(0)
	v_cmp_gt_u64_e64 s[18:19], v[192:193], v[14:15]
	v_cmp_gt_u64_e64 s[20:21], v[194:195], v[16:17]
	s_xor_b64 s[14:15], s[14:15], s[12:13]
	s_xor_b64 s[16:17], s[16:17], s[12:13]
	s_xor_b64 s[18:19], s[18:19], s[12:13]
	s_xor_b64 s[20:21], s[20:21], s[12:13]
	v_cndmask_b32_e64 v188, v188, v10, s[14:15]
	v_cndmask_b32_e64 v189, v189, v11, s[14:15]
	v_cndmask_b32_e64 v190, v190, v12, s[16:17]
	v_cndmask_b32_e64 v191, v191, v13, s[16:17]
	v_cndmask_b32_e64 v192, v192, v14, s[18:19]
	v_cndmask_b32_e64 v193, v193, v15, s[18:19]
	v_cndmask_b32_e64 v194, v194, v16, s[20:21]
	v_cndmask_b32_e64 v195, v195, v17, s[20:21]
	s_not_b64 s[12:13], s[10:11]
	s_bitcmp1_b32 s22, 2
	s_cselect_b64 s[12:13], s[10:11], s[12:13]
	ds_bpermute_b32 v10, v201, v188
	ds_bpermute_b32 v11, v201, v189
	ds_bpermute_b32 v12, v201, v190
	ds_bpermute_b32 v13, v201, v191
	ds_bpermute_b32 v14, v201, v192
	ds_bpermute_b32 v15, v201, v193
	ds_bpermute_b32 v16, v201, v194
	ds_bpermute_b32 v17, v201, v195
	s_waitcnt lgkmcnt(6)
	v_cmp_gt_u64_e64 s[14:15], v[188:189], v[10:11]
	s_waitcnt lgkmcnt(4)
	v_cmp_gt_u64_e64 s[16:17], v[190:191], v[12:13]
	s_waitcnt lgkmcnt(2)
	v_cmp_gt_u64_e64 s[18:19], v[192:193], v[14:15]
	s_waitcnt lgkmcnt(0)
	v_cmp_gt_u64_e64 s[20:21], v[194:195], v[16:17]
	s_xor_b64 s[14:15], s[14:15], s[12:13]
	s_xor_b64 s[16:17], s[16:17], s[12:13]
	s_xor_b64 s[18:19], s[18:19], s[12:13]
	s_xor_b64 s[20:21], s[20:21], s[12:13]
	v_cndmask_b32_e64 v188, v188, v10, s[14:15]
	v_cndmask_b32_e64 v189, v189, v11, s[14:15]
	v_cndmask_b32_e64 v190, v190, v12, s[16:17]
	v_cndmask_b32_e64 v191, v191, v13, s[16:17]
	v_cndmask_b32_e64 v192, v192, v14, s[18:19]
	v_cndmask_b32_e64 v193, v193, v15, s[18:19]
	v_cndmask_b32_e64 v194, v194, v16, s[20:21]
	v_cndmask_b32_e64 v195, v195, v17, s[20:21]
	s_not_b64 s[12:13], s[8:9]
	s_bitcmp1_b32 s22, 2
	s_cselect_b64 s[12:13], s[8:9], s[12:13]
	ds_bpermute_b32 v10, v200, v188
	ds_bpermute_b32 v11, v200, v189
	ds_bpermute_b32 v12, v200, v190
	ds_bpermute_b32 v13, v200, v191
	ds_bpermute_b32 v14, v200, v192
	ds_bpermute_b32 v15, v200, v193
	ds_bpermute_b32 v16, v200, v194
	ds_bpermute_b32 v17, v200, v195
	s_waitcnt lgkmcnt(6)
	v_cmp_gt_u64_e64 s[14:15], v[188:189], v[10:11]
	s_waitcnt lgkmcnt(4)
	v_cmp_gt_u64_e64 s[16:17], v[190:191], v[12:13]
	s_waitcnt lgkmcnt(2)
	v_cmp_gt_u64_e64 s[18:19], v[192:193], v[14:15]
	s_waitcnt lgkmcnt(0)
	v_cmp_gt_u64_e64 s[20:21], v[194:195], v[16:17]
	s_xor_b64 s[14:15], s[14:15], s[12:13]
	s_xor_b64 s[16:17], s[16:17], s[12:13]
	s_xor_b64 s[18:19], s[18:19], s[12:13]
	s_xor_b64 s[20:21], s[20:21], s[12:13]
	v_cndmask_b32_e64 v188, v188, v10, s[14:15]
	v_cndmask_b32_e64 v189, v189, v11, s[14:15]
	v_cndmask_b32_e64 v190, v190, v12, s[16:17]
	v_cndmask_b32_e64 v191, v191, v13, s[16:17]
	v_cndmask_b32_e64 v192, v192, v14, s[18:19]
	v_cndmask_b32_e64 v193, v193, v15, s[18:19]
	v_cndmask_b32_e64 v194, v194, v16, s[20:21]
	v_cndmask_b32_e64 v195, v195, v17, s[20:21]
	s_not_b64 s[12:13], s[6:7]
	s_bitcmp1_b32 s22, 2
	s_cselect_b64 s[12:13], s[6:7], s[12:13]
	ds_bpermute_b32 v10, v199, v188
	ds_bpermute_b32 v11, v199, v189
	ds_bpermute_b32 v12, v199, v190
	ds_bpermute_b32 v13, v199, v191
	ds_bpermute_b32 v14, v199, v192
	ds_bpermute_b32 v15, v199, v193
	ds_bpermute_b32 v16, v199, v194
	ds_bpermute_b32 v17, v199, v195
	s_waitcnt lgkmcnt(6)
	v_cmp_gt_u64_e64 s[14:15], v[188:189], v[10:11]
	s_waitcnt lgkmcnt(4)
	v_cmp_gt_u64_e64 s[16:17], v[190:191], v[12:13]
	s_waitcnt lgkmcnt(2)
	v_cmp_gt_u64_e64 s[18:19], v[192:193], v[14:15]
	s_waitcnt lgkmcnt(0)
	v_cmp_gt_u64_e64 s[20:21], v[194:195], v[16:17]
	s_xor_b64 s[14:15], s[14:15], s[12:13]
	s_xor_b64 s[16:17], s[16:17], s[12:13]
	s_xor_b64 s[18:19], s[18:19], s[12:13]
	s_xor_b64 s[20:21], s[20:21], s[12:13]
	v_cndmask_b32_e64 v188, v188, v10, s[14:15]
	v_cndmask_b32_e64 v189, v189, v11, s[14:15]
	v_cndmask_b32_e64 v190, v190, v12, s[16:17]
	v_cndmask_b32_e64 v191, v191, v13, s[16:17]
	v_cndmask_b32_e64 v192, v192, v14, s[18:19]
	v_cndmask_b32_e64 v193, v193, v15, s[18:19]
	v_cndmask_b32_e64 v194, v194, v16, s[20:21]
	v_cndmask_b32_e64 v195, v195, v17, s[20:21]
	s_not_b64 s[12:13], s[4:5]
	s_bitcmp1_b32 s22, 2
	s_cselect_b64 s[12:13], s[4:5], s[12:13]
	ds_bpermute_b32 v10, v198, v188
	ds_bpermute_b32 v11, v198, v189
	ds_bpermute_b32 v12, v198, v190
	ds_bpermute_b32 v13, v198, v191
	ds_bpermute_b32 v14, v198, v192
	ds_bpermute_b32 v15, v198, v193
	ds_bpermute_b32 v16, v198, v194
	ds_bpermute_b32 v17, v198, v195
	s_waitcnt lgkmcnt(6)
	v_cmp_gt_u64_e64 s[14:15], v[188:189], v[10:11]
	s_waitcnt lgkmcnt(4)
	v_cmp_gt_u64_e64 s[16:17], v[190:191], v[12:13]
	s_waitcnt lgkmcnt(2)
	v_cmp_gt_u64_e64 s[18:19], v[192:193], v[14:15]
	s_waitcnt lgkmcnt(0)
	v_cmp_gt_u64_e64 s[20:21], v[194:195], v[16:17]
	s_xor_b64 s[14:15], s[14:15], s[12:13]
	s_xor_b64 s[16:17], s[16:17], s[12:13]
	s_xor_b64 s[18:19], s[18:19], s[12:13]
	s_xor_b64 s[20:21], s[20:21], s[12:13]
	v_cndmask_b32_e64 v188, v188, v10, s[14:15]
	v_cndmask_b32_e64 v189, v189, v11, s[14:15]
	v_cndmask_b32_e64 v190, v190, v12, s[16:17]
	v_cndmask_b32_e64 v191, v191, v13, s[16:17]
	v_cndmask_b32_e64 v192, v192, v14, s[18:19]
	v_cndmask_b32_e64 v193, v193, v15, s[18:19]
	v_cndmask_b32_e64 v194, v194, v16, s[20:21]
	v_cndmask_b32_e64 v195, v195, v17, s[20:21]
	s_not_b64 s[12:13], s[2:3]
	s_bitcmp1_b32 s22, 2
	s_cselect_b64 s[12:13], s[2:3], s[12:13]
	ds_bpermute_b32 v10, v197, v188
	ds_bpermute_b32 v11, v197, v189
	ds_bpermute_b32 v12, v197, v190
	ds_bpermute_b32 v13, v197, v191
	ds_bpermute_b32 v14, v197, v192
	ds_bpermute_b32 v15, v197, v193
	ds_bpermute_b32 v16, v197, v194
	ds_bpermute_b32 v17, v197, v195
	s_waitcnt lgkmcnt(6)
	v_cmp_gt_u64_e64 s[14:15], v[188:189], v[10:11]
	s_waitcnt lgkmcnt(4)
	v_cmp_gt_u64_e64 s[16:17], v[190:191], v[12:13]
	s_waitcnt lgkmcnt(2)
	v_cmp_gt_u64_e64 s[18:19], v[192:193], v[14:15]
	s_waitcnt lgkmcnt(0)
	v_cmp_gt_u64_e64 s[20:21], v[194:195], v[16:17]
	s_xor_b64 s[14:15], s[14:15], s[12:13]
	s_xor_b64 s[16:17], s[16:17], s[12:13]
	s_xor_b64 s[18:19], s[18:19], s[12:13]
	s_xor_b64 s[20:21], s[20:21], s[12:13]
	v_cndmask_b32_e64 v188, v188, v10, s[14:15]
	v_cndmask_b32_e64 v189, v189, v11, s[14:15]
	v_cndmask_b32_e64 v190, v190, v12, s[16:17]
	v_cndmask_b32_e64 v191, v191, v13, s[16:17]
	v_cndmask_b32_e64 v192, v192, v14, s[18:19]
	v_cndmask_b32_e64 v193, v193, v15, s[18:19]
	v_cndmask_b32_e64 v194, v194, v16, s[20:21]
	v_cndmask_b32_e64 v195, v195, v17, s[20:21]
	s_not_b64 s[12:13], s[0:1]
	s_bitcmp1_b32 s22, 2
	s_cselect_b64 s[12:13], s[0:1], s[12:13]
	ds_bpermute_b32 v10, v196, v188
	ds_bpermute_b32 v11, v196, v189
	ds_bpermute_b32 v12, v196, v190
	ds_bpermute_b32 v13, v196, v191
	ds_bpermute_b32 v14, v196, v192
	ds_bpermute_b32 v15, v196, v193
	ds_bpermute_b32 v16, v196, v194
	ds_bpermute_b32 v17, v196, v195
	s_waitcnt lgkmcnt(6)
	v_cmp_gt_u64_e64 s[14:15], v[188:189], v[10:11]
	s_waitcnt lgkmcnt(4)
	v_cmp_gt_u64_e64 s[16:17], v[190:191], v[12:13]
	s_waitcnt lgkmcnt(2)
	v_cmp_gt_u64_e64 s[18:19], v[192:193], v[14:15]
	s_waitcnt lgkmcnt(0)
	v_cmp_gt_u64_e64 s[20:21], v[194:195], v[16:17]
	s_xor_b64 s[14:15], s[14:15], s[12:13]
	s_xor_b64 s[16:17], s[16:17], s[12:13]
	s_xor_b64 s[18:19], s[18:19], s[12:13]
	s_xor_b64 s[20:21], s[20:21], s[12:13]
	v_cndmask_b32_e64 v188, v188, v10, s[14:15]
	v_cndmask_b32_e64 v189, v189, v11, s[14:15]
	v_cndmask_b32_e64 v190, v190, v12, s[16:17]
	v_cndmask_b32_e64 v191, v191, v13, s[16:17]
	v_cndmask_b32_e64 v192, v192, v14, s[18:19]
	v_cndmask_b32_e64 v193, v193, v15, s[18:19]
	v_cndmask_b32_e64 v194, v194, v16, s[20:21]
	v_cndmask_b32_e64 v195, v195, v17, s[20:21]
	s_bitcmp0_b32 s22, 2
	s_cselect_b64 s[12:13], -1, 0
	v_cmp_gt_u64_e64 s[14:15], v[188:189], v[192:193]
	v_cmp_gt_u64_e64 s[16:17], v[190:191], v[194:195]
	s_xor_b64 s[14:15], s[14:15], s[12:13]
	s_xor_b64 s[16:17], s[16:17], s[12:13]
	v_cndmask_b32_e64 v2, v188, v192, s[14:15]
	v_cndmask_b32_e64 v3, v189, v193, s[14:15]
	v_cndmask_b32_e64 v6, v192, v188, s[14:15]
	v_cndmask_b32_e64 v7, v193, v189, s[14:15]
	v_cndmask_b32_e64 v4, v190, v194, s[16:17]
	v_cndmask_b32_e64 v5, v191, v195, s[16:17]
	v_cndmask_b32_e64 v8, v194, v190, s[16:17]
	v_cndmask_b32_e64 v9, v195, v191, s[16:17]
	s_bitcmp0_b32 s22, 2
	s_cselect_b64 s[12:13], -1, 0
	v_cmp_gt_u64_e64 s[14:15], v[2:3], v[4:5]
	v_cmp_gt_u64_e64 s[16:17], v[6:7], v[8:9]
	s_xor_b64 s[14:15], s[14:15], s[12:13]
	s_xor_b64 s[16:17], s[16:17], s[12:13]
	v_cndmask_b32_e64 v188, v2, v4, s[14:15]
	v_cndmask_b32_e64 v189, v3, v5, s[14:15]
	v_cndmask_b32_e64 v190, v4, v2, s[14:15]
	v_cndmask_b32_e64 v191, v5, v3, s[14:15]
	v_cndmask_b32_e64 v192, v6, v8, s[16:17]
	v_cndmask_b32_e64 v193, v7, v9, s[16:17]
	v_cndmask_b32_e64 v194, v8, v6, s[16:17]
	v_cndmask_b32_e64 v195, v9, v7, s[16:17]
	s_bitcmp0_b32 s22, 2
	s_cselect_b64 s[12:13], -1, 0
	ds_write_b128 v202, v[188:191] offset:16384
	ds_write_b128 v202, v[192:195] offset:16400
	s_waitcnt lgkmcnt(0)
	s_barrier
	ds_read_b128 v[10:13], v205 offset:16384
	ds_read_b128 v[14:17], v205 offset:16400
	s_waitcnt lgkmcnt(1)
	v_cmp_gt_u64_e64 s[14:15], v[188:189], v[10:11]
	v_cmp_gt_u64_e64 s[16:17], v[190:191], v[12:13]
	s_waitcnt lgkmcnt(0)
	v_cmp_gt_u64_e64 s[18:19], v[192:193], v[14:15]
	v_cmp_gt_u64_e64 s[20:21], v[194:195], v[16:17]
	s_xor_b64 s[14:15], s[14:15], s[12:13]
	s_xor_b64 s[16:17], s[16:17], s[12:13]
	s_xor_b64 s[18:19], s[18:19], s[12:13]
	s_xor_b64 s[20:21], s[20:21], s[12:13]
	v_cndmask_b32_e64 v188, v188, v10, s[14:15]
	v_cndmask_b32_e64 v189, v189, v11, s[14:15]
	v_cndmask_b32_e64 v190, v190, v12, s[16:17]
	v_cndmask_b32_e64 v191, v191, v13, s[16:17]
	v_cndmask_b32_e64 v192, v192, v14, s[18:19]
	v_cndmask_b32_e64 v193, v193, v15, s[18:19]
	v_cndmask_b32_e64 v194, v194, v16, s[20:21]
	v_cndmask_b32_e64 v195, v195, v17, s[20:21]
	s_bitcmp0_b32 s22, 1
	s_cselect_b64 s[12:13], -1, 0
	ds_write_b128 v202, v[188:191]
	ds_write_b128 v202, v[192:195] offset:16
	s_waitcnt lgkmcnt(0)
	s_barrier
	ds_read_b128 v[10:13], v204
	ds_read_b128 v[14:17], v204 offset:16
	s_waitcnt lgkmcnt(1)
	v_cmp_gt_u64_e64 s[14:15], v[188:189], v[10:11]
	v_cmp_gt_u64_e64 s[16:17], v[190:191], v[12:13]
	s_waitcnt lgkmcnt(0)
	v_cmp_gt_u64_e64 s[18:19], v[192:193], v[14:15]
	v_cmp_gt_u64_e64 s[20:21], v[194:195], v[16:17]
	s_xor_b64 s[14:15], s[14:15], s[12:13]
	s_xor_b64 s[16:17], s[16:17], s[12:13]
	s_xor_b64 s[18:19], s[18:19], s[12:13]
	s_xor_b64 s[20:21], s[20:21], s[12:13]
	v_cndmask_b32_e64 v188, v188, v10, s[14:15]
	v_cndmask_b32_e64 v189, v189, v11, s[14:15]
	v_cndmask_b32_e64 v190, v190, v12, s[16:17]
	v_cndmask_b32_e64 v191, v191, v13, s[16:17]
	v_cndmask_b32_e64 v192, v192, v14, s[18:19]
	v_cndmask_b32_e64 v193, v193, v15, s[18:19]
	v_cndmask_b32_e64 v194, v194, v16, s[20:21]
	v_cndmask_b32_e64 v195, v195, v17, s[20:21]
	s_bitcmp0_b32 s22, 0
	s_cselect_b64 s[12:13], -1, 0
	ds_write_b128 v202, v[188:191] offset:16384
	ds_write_b128 v202, v[192:195] offset:16400
	s_waitcnt lgkmcnt(0)
	s_barrier
	ds_read_b128 v[10:13], v203 offset:16384
	ds_read_b128 v[14:17], v203 offset:16400
	s_waitcnt lgkmcnt(1)
	v_cmp_gt_u64_e64 s[14:15], v[188:189], v[10:11]
	v_cmp_gt_u64_e64 s[16:17], v[190:191], v[12:13]
	s_waitcnt lgkmcnt(0)
	v_cmp_gt_u64_e64 s[18:19], v[192:193], v[14:15]
	v_cmp_gt_u64_e64 s[20:21], v[194:195], v[16:17]
	s_xor_b64 s[14:15], s[14:15], s[12:13]
	s_xor_b64 s[16:17], s[16:17], s[12:13]
	s_xor_b64 s[18:19], s[18:19], s[12:13]
	s_xor_b64 s[20:21], s[20:21], s[12:13]
	v_cndmask_b32_e64 v188, v188, v10, s[14:15]
	v_cndmask_b32_e64 v189, v189, v11, s[14:15]
	v_cndmask_b32_e64 v190, v190, v12, s[16:17]
	v_cndmask_b32_e64 v191, v191, v13, s[16:17]
	v_cndmask_b32_e64 v192, v192, v14, s[18:19]
	v_cndmask_b32_e64 v193, v193, v15, s[18:19]
	v_cndmask_b32_e64 v194, v194, v16, s[20:21]
	v_cndmask_b32_e64 v195, v195, v17, s[20:21]
	s_not_b64 s[12:13], s[10:11]
	ds_bpermute_b32 v10, v201, v188
	ds_bpermute_b32 v11, v201, v189
	ds_bpermute_b32 v12, v201, v190
	ds_bpermute_b32 v13, v201, v191
	ds_bpermute_b32 v14, v201, v192
	ds_bpermute_b32 v15, v201, v193
	ds_bpermute_b32 v16, v201, v194
	ds_bpermute_b32 v17, v201, v195
	s_waitcnt lgkmcnt(6)
	v_cmp_gt_u64_e64 s[14:15], v[188:189], v[10:11]
	s_waitcnt lgkmcnt(4)
	v_cmp_gt_u64_e64 s[16:17], v[190:191], v[12:13]
	s_waitcnt lgkmcnt(2)
	v_cmp_gt_u64_e64 s[18:19], v[192:193], v[14:15]
	s_waitcnt lgkmcnt(0)
	v_cmp_gt_u64_e64 s[20:21], v[194:195], v[16:17]
	s_xor_b64 s[14:15], s[14:15], s[12:13]
	s_xor_b64 s[16:17], s[16:17], s[12:13]
	s_xor_b64 s[18:19], s[18:19], s[12:13]
	s_xor_b64 s[20:21], s[20:21], s[12:13]
	v_cndmask_b32_e64 v188, v188, v10, s[14:15]
	v_cndmask_b32_e64 v189, v189, v11, s[14:15]
	v_cndmask_b32_e64 v190, v190, v12, s[16:17]
	v_cndmask_b32_e64 v191, v191, v13, s[16:17]
	v_cndmask_b32_e64 v192, v192, v14, s[18:19]
	v_cndmask_b32_e64 v193, v193, v15, s[18:19]
	v_cndmask_b32_e64 v194, v194, v16, s[20:21]
	v_cndmask_b32_e64 v195, v195, v17, s[20:21]
	s_not_b64 s[12:13], s[8:9]
	ds_bpermute_b32 v10, v200, v188
	ds_bpermute_b32 v11, v200, v189
	ds_bpermute_b32 v12, v200, v190
	ds_bpermute_b32 v13, v200, v191
	ds_bpermute_b32 v14, v200, v192
	ds_bpermute_b32 v15, v200, v193
	ds_bpermute_b32 v16, v200, v194
	ds_bpermute_b32 v17, v200, v195
	s_waitcnt lgkmcnt(6)
	v_cmp_gt_u64_e64 s[14:15], v[188:189], v[10:11]
	s_waitcnt lgkmcnt(4)
	v_cmp_gt_u64_e64 s[16:17], v[190:191], v[12:13]
	s_waitcnt lgkmcnt(2)
	v_cmp_gt_u64_e64 s[18:19], v[192:193], v[14:15]
	s_waitcnt lgkmcnt(0)
	v_cmp_gt_u64_e64 s[20:21], v[194:195], v[16:17]
	s_xor_b64 s[14:15], s[14:15], s[12:13]
	s_xor_b64 s[16:17], s[16:17], s[12:13]
	s_xor_b64 s[18:19], s[18:19], s[12:13]
	s_xor_b64 s[20:21], s[20:21], s[12:13]
	v_cndmask_b32_e64 v188, v188, v10, s[14:15]
	v_cndmask_b32_e64 v189, v189, v11, s[14:15]
	v_cndmask_b32_e64 v190, v190, v12, s[16:17]
	v_cndmask_b32_e64 v191, v191, v13, s[16:17]
	v_cndmask_b32_e64 v192, v192, v14, s[18:19]
	v_cndmask_b32_e64 v193, v193, v15, s[18:19]
	v_cndmask_b32_e64 v194, v194, v16, s[20:21]
	v_cndmask_b32_e64 v195, v195, v17, s[20:21]
	s_not_b64 s[12:13], s[6:7]
	ds_bpermute_b32 v10, v199, v188
	ds_bpermute_b32 v11, v199, v189
	ds_bpermute_b32 v12, v199, v190
	ds_bpermute_b32 v13, v199, v191
	ds_bpermute_b32 v14, v199, v192
	ds_bpermute_b32 v15, v199, v193
	ds_bpermute_b32 v16, v199, v194
	ds_bpermute_b32 v17, v199, v195
	s_waitcnt lgkmcnt(6)
	v_cmp_gt_u64_e64 s[14:15], v[188:189], v[10:11]
	s_waitcnt lgkmcnt(4)
	v_cmp_gt_u64_e64 s[16:17], v[190:191], v[12:13]
	s_waitcnt lgkmcnt(2)
	v_cmp_gt_u64_e64 s[18:19], v[192:193], v[14:15]
	s_waitcnt lgkmcnt(0)
	v_cmp_gt_u64_e64 s[20:21], v[194:195], v[16:17]
	s_xor_b64 s[14:15], s[14:15], s[12:13]
	s_xor_b64 s[16:17], s[16:17], s[12:13]
	s_xor_b64 s[18:19], s[18:19], s[12:13]
	s_xor_b64 s[20:21], s[20:21], s[12:13]
	v_cndmask_b32_e64 v188, v188, v10, s[14:15]
	v_cndmask_b32_e64 v189, v189, v11, s[14:15]
	v_cndmask_b32_e64 v190, v190, v12, s[16:17]
	v_cndmask_b32_e64 v191, v191, v13, s[16:17]
	v_cndmask_b32_e64 v192, v192, v14, s[18:19]
	v_cndmask_b32_e64 v193, v193, v15, s[18:19]
	v_cndmask_b32_e64 v194, v194, v16, s[20:21]
	v_cndmask_b32_e64 v195, v195, v17, s[20:21]
	s_not_b64 s[12:13], s[4:5]
	ds_bpermute_b32 v10, v198, v188
	ds_bpermute_b32 v11, v198, v189
	ds_bpermute_b32 v12, v198, v190
	ds_bpermute_b32 v13, v198, v191
	ds_bpermute_b32 v14, v198, v192
	ds_bpermute_b32 v15, v198, v193
	ds_bpermute_b32 v16, v198, v194
	ds_bpermute_b32 v17, v198, v195
	s_waitcnt lgkmcnt(6)
	v_cmp_gt_u64_e64 s[14:15], v[188:189], v[10:11]
	s_waitcnt lgkmcnt(4)
	v_cmp_gt_u64_e64 s[16:17], v[190:191], v[12:13]
	s_waitcnt lgkmcnt(2)
	v_cmp_gt_u64_e64 s[18:19], v[192:193], v[14:15]
	s_waitcnt lgkmcnt(0)
	v_cmp_gt_u64_e64 s[20:21], v[194:195], v[16:17]
	s_xor_b64 s[14:15], s[14:15], s[12:13]
	s_xor_b64 s[16:17], s[16:17], s[12:13]
	s_xor_b64 s[18:19], s[18:19], s[12:13]
	s_xor_b64 s[20:21], s[20:21], s[12:13]
	v_cndmask_b32_e64 v188, v188, v10, s[14:15]
	v_cndmask_b32_e64 v189, v189, v11, s[14:15]
	v_cndmask_b32_e64 v190, v190, v12, s[16:17]
	v_cndmask_b32_e64 v191, v191, v13, s[16:17]
	v_cndmask_b32_e64 v192, v192, v14, s[18:19]
	v_cndmask_b32_e64 v193, v193, v15, s[18:19]
	v_cndmask_b32_e64 v194, v194, v16, s[20:21]
	v_cndmask_b32_e64 v195, v195, v17, s[20:21]
	s_not_b64 s[12:13], s[2:3]
	ds_bpermute_b32 v10, v197, v188
	ds_bpermute_b32 v11, v197, v189
	ds_bpermute_b32 v12, v197, v190
	ds_bpermute_b32 v13, v197, v191
	ds_bpermute_b32 v14, v197, v192
	ds_bpermute_b32 v15, v197, v193
	ds_bpermute_b32 v16, v197, v194
	ds_bpermute_b32 v17, v197, v195
	s_waitcnt lgkmcnt(6)
	v_cmp_gt_u64_e64 s[14:15], v[188:189], v[10:11]
	s_waitcnt lgkmcnt(4)
	v_cmp_gt_u64_e64 s[16:17], v[190:191], v[12:13]
	s_waitcnt lgkmcnt(2)
	v_cmp_gt_u64_e64 s[18:19], v[192:193], v[14:15]
	s_waitcnt lgkmcnt(0)
	v_cmp_gt_u64_e64 s[20:21], v[194:195], v[16:17]
	s_xor_b64 s[14:15], s[14:15], s[12:13]
	s_xor_b64 s[16:17], s[16:17], s[12:13]
	s_xor_b64 s[18:19], s[18:19], s[12:13]
	s_xor_b64 s[20:21], s[20:21], s[12:13]
	v_cndmask_b32_e64 v188, v188, v10, s[14:15]
	v_cndmask_b32_e64 v189, v189, v11, s[14:15]
	v_cndmask_b32_e64 v190, v190, v12, s[16:17]
	v_cndmask_b32_e64 v191, v191, v13, s[16:17]
	v_cndmask_b32_e64 v192, v192, v14, s[18:19]
	v_cndmask_b32_e64 v193, v193, v15, s[18:19]
	v_cndmask_b32_e64 v194, v194, v16, s[20:21]
	v_cndmask_b32_e64 v195, v195, v17, s[20:21]
	s_not_b64 s[12:13], s[0:1]
	ds_bpermute_b32 v10, v196, v188
	ds_bpermute_b32 v11, v196, v189
	ds_bpermute_b32 v12, v196, v190
	ds_bpermute_b32 v13, v196, v191
	ds_bpermute_b32 v14, v196, v192
	ds_bpermute_b32 v15, v196, v193
	ds_bpermute_b32 v16, v196, v194
	ds_bpermute_b32 v17, v196, v195
	s_waitcnt lgkmcnt(6)
	v_cmp_gt_u64_e64 s[14:15], v[188:189], v[10:11]
	s_waitcnt lgkmcnt(4)
	v_cmp_gt_u64_e64 s[16:17], v[190:191], v[12:13]
	s_waitcnt lgkmcnt(2)
	v_cmp_gt_u64_e64 s[18:19], v[192:193], v[14:15]
	s_waitcnt lgkmcnt(0)
	v_cmp_gt_u64_e64 s[20:21], v[194:195], v[16:17]
	s_xor_b64 s[14:15], s[14:15], s[12:13]
	s_xor_b64 s[16:17], s[16:17], s[12:13]
	s_xor_b64 s[18:19], s[18:19], s[12:13]
	s_xor_b64 s[20:21], s[20:21], s[12:13]
	v_cndmask_b32_e64 v188, v188, v10, s[14:15]
	v_cndmask_b32_e64 v189, v189, v11, s[14:15]
	v_cndmask_b32_e64 v190, v190, v12, s[16:17]
	v_cndmask_b32_e64 v191, v191, v13, s[16:17]
	v_cndmask_b32_e64 v192, v192, v14, s[18:19]
	v_cndmask_b32_e64 v193, v193, v15, s[18:19]
	v_cndmask_b32_e64 v194, v194, v16, s[20:21]
	v_cndmask_b32_e64 v195, v195, v17, s[20:21]
	s_mov_b64 s[12:13], -1
	v_cmp_gt_u64_e64 s[14:15], v[188:189], v[192:193]
	v_cmp_gt_u64_e64 s[16:17], v[190:191], v[194:195]
	s_xor_b64 s[14:15], s[14:15], s[12:13]
	s_xor_b64 s[16:17], s[16:17], s[12:13]
	v_cndmask_b32_e64 v2, v188, v192, s[14:15]
	v_cndmask_b32_e64 v3, v189, v193, s[14:15]
	v_cndmask_b32_e64 v6, v192, v188, s[14:15]
	v_cndmask_b32_e64 v7, v193, v189, s[14:15]
	v_cndmask_b32_e64 v4, v190, v194, s[16:17]
	v_cndmask_b32_e64 v5, v191, v195, s[16:17]
	v_cndmask_b32_e64 v8, v194, v190, s[16:17]
	v_cndmask_b32_e64 v9, v195, v191, s[16:17]
	s_mov_b64 s[12:13], -1
	v_cmp_gt_u64_e64 s[14:15], v[2:3], v[4:5]
	v_cmp_gt_u64_e64 s[16:17], v[6:7], v[8:9]
	s_xor_b64 s[14:15], s[14:15], s[12:13]
	s_xor_b64 s[16:17], s[16:17], s[12:13]
	v_cndmask_b32_e64 v188, v2, v4, s[14:15]
	v_cndmask_b32_e64 v189, v3, v5, s[14:15]
	v_cndmask_b32_e64 v190, v4, v2, s[14:15]
	v_cndmask_b32_e64 v191, v5, v3, s[14:15]
	v_cndmask_b32_e64 v192, v6, v8, s[16:17]
	v_cndmask_b32_e64 v193, v7, v9, s[16:17]
	v_cndmask_b32_e64 v194, v8, v6, s[16:17]
	v_cndmask_b32_e64 v195, v9, v7, s[16:17]
.Ltks_short:
	s_lshr_b32 s31, s26, 2
	v_cmp_gt_u32_e64 s[14:15], s31, v18
	v_cmp_gt_u32_e64 s[16:17], s27, v18
	v_lshlrev_b32_e32 v206, 2, v18
	v_not_b32_e32 v10, v188
	v_not_b32_e32 v11, v190
	v_not_b32_e32 v12, v192
	v_not_b32_e32 v13, v194
	v_lshl_add_u32 v210, v10, 6, s33
	v_lshl_add_u32 v211, v11, 6, s33
	v_lshl_add_u32 v212, v12, 6, s33
	v_lshl_add_u32 v213, v13, 6, s33
	v_mov_b32_e32 v214, v206
	v_add_u32_e32 v215, 1, v206
	v_add_u32_e32 v216, 2, v206
	v_add_u32_e32 v217, 3, v206
	v_cndmask_b32_e64 v214, -1, v214, s[16:17]
	v_cndmask_b32_e64 v215, -1, v215, s[16:17]
	v_cndmask_b32_e64 v216, -1, v216, s[16:17]
	v_cndmask_b32_e64 v217, -1, v217, s[16:17]
	v_add_u32_e32 v10, s28, v10
	v_add_u32_e32 v11, s28, v11
	v_add_u32_e32 v12, s28, v12
	v_add_u32_e32 v13, s28, v13
	s_mul_i32 s31, s30, 0x1200
	s_add_i32 s31, s31, s29
	s_lshl_b32 s31, s31, 2
	v_lshl_add_u32 v207, v18, 4, s31
	s_add_u32 s98, s34, 0x700000
	s_addc_u32 s99, s35, 0
	s_and_saveexec_b64 s[20:21], s[14:15]
	s_nop 0
	global_store_dword v210, v214, s[98:99]
	global_store_dword v211, v215, s[98:99]
	global_store_dword v212, v216, s[98:99]
	global_store_dword v213, v217, s[98:99]
	s_add_u32 s98, s34, 0xa00000
	s_addc_u32 s99, s35, 0
	s_and_b64 exec, exec, s[16:17]
	s_nop 0
	global_store_dwordx4 v207, v[10:13], s[98:99]
	s_nop 1
	s_mov_b64 exec, -1
	s_add_i32 s24, s24, s47
	s_branch .Ltks_item
